# MoE GEMM main loops: phase pairs merged (16 MFMAs per segment), half the workgroup barriers per iteration; refill DMA of B half 0 moved behind the next barrier
# speedup vs baseline: 1.0020x; 1.0017x over previous
.LBB0_2874:
	s_and_b32 s0, s20, 3
	s_lshl_b32 s1, s24, 13
	s_lshl_b32 s2, s0, 12
	s_add_i32 s53, s42, 0x18000
	s_mov_b64 s[20:21], 0x80
	s_add_i32 s55, s42, 0x1a000
	v_lshl_add_u64 v[6:7], v[6:7], 0, s[20:21]
	s_mov_b32 m0, s53
	s_add_u32 s22, s3, 0x1b3c3180
	s_waitcnt vmcnt(0)
	s_barrier
	global_load_lds_dwordx4 v[6:7], off
	v_lshl_add_u64 v[4:5], v[4:5], 0, s[20:21]
	s_mov_b32 m0, s55
	s_addc_u32 s23, s38, 0
	s_add_i32 s64, s42, 0x8000
	s_add_i32 s65, s42, 0xa000
	global_load_lds_dwordx4 v[4:5], off
	v_lshl_add_u64 v[4:5], s[22:23], 0, v[150:151]
	s_mov_b32 m0, s64
	s_add_u32 s26, s30, 0x20080
	global_load_lds_dwordx4 v[4:5], off
	v_lshl_add_u64 v[4:5], s[22:23], 0, v[158:159]
	s_mov_b32 m0, s65
	s_addc_u32 s27, s31, 0
	s_add_i32 s68, s42, 0x1c000
	global_load_lds_dwordx4 v[4:5], off
	v_lshl_add_u64 v[4:5], s[26:27], 0, v[148:149]
	s_mov_b32 m0, s68
	s_add_i32 s69, s42, 0x1e000
	global_load_lds_dwordx4 v[4:5], off
	v_lshl_add_u64 v[4:5], s[26:27], 0, v[146:147]
	s_mov_b32 m0, s69
	v_lshlrev_b32_e32 v7, 2, v8
	global_load_lds_dwordx4 v[4:5], off
	v_and_b32_e32 v4, 3, v9
	v_lshlrev_b32_e32 v5, 4, v4
	v_lshlrev_b32_e32 v6, 6, v8
	v_and_b32_e32 v7, 32, v7
	v_bitop3_b32 v5, v6, v7, v5 bitop3:0x36
	s_waitcnt vmcnt(6)
	s_add_i32 s2, s2, 0
	v_lshlrev_b32_e32 v4, 2, v4
	v_lshl_add_u64 v[152:153], v[2:3], 2, s[12:13]
	v_add_u32_e32 v2, s2, v5
	v_add_u32_e32 v3, 0, v5
	v_lshl_or_b32 v183, s0, 4, v4
	v_readlane_b32 s0, v252, 8
	v_lshl_or_b32 v159, s24, 6, v8
	v_add_u32_e32 v179, 0x10000, v2
	v_add_u32_e32 v180, 0x14000, v2
	v_add_u32_e32 v181, 0x18000, v2
	v_add_u32_e32 v182, 0x1c000, v2
	v_add_u32_e32 v184, 0x10400, v2
	v_add_u32_e32 v185, 0x10800, v2
	v_add_u32_e32 v186, 0x10c00, v2
	v_add_u32_e32 v187, 0x14400, v2
	v_add_u32_e32 v188, 0x14800, v2
	v_add_u32_e32 v189, 0x14c00, v2
	v_add_u32_e32 v190, 0x18400, v2
	v_add_u32_e32 v191, 0x18800, v2
	v_add_u32_e32 v192, 0x18c00, v2
	v_add_u32_e32 v193, 0x1c400, v2
	v_add_u32_e32 v194, 0x1c800, v2
	v_add_u32_e32 v195, 0x1cc00, v2
	s_ashr_i32 s70, s0, 31
	v_mov_b64_e32 v[154:155], 0x1600
	v_mov_b64_e32 v[156:157], 0x15ff
	v_add_u32_e32 v196, s1, v3
	s_mov_b32 s71, 0xc3dc0000
	s_movk_i32 s72, 0xb00
	v_mov_b32_e32 v197, 0x43dc0000
	v_mov_b32_e32 v200, v150
	s_barrier
	s_waitcnt vmcnt(0)

.LBB0_2878:
	ds_read2_b32 v[2:3], v178 offset1:16
	s_add_u32 s0, s3, s30
	s_addc_u32 s1, s38, s31
	s_add_u32 s0, s0, 0x1b3c3200
	ds_read2_b32 v[168:169], v178 offset0:32 offset1:48
	s_waitcnt lgkmcnt(0)
	v_lshl_add_u32 v161, v2, 10, v1
	v_lshl_add_u32 v163, v3, 10, v176
	ds_read_b128 v[2:5], v179
	ds_read_b128 v[6:9], v184
	ds_read_b128 v[10:13], v185
	ds_read_b128 v[14:17], v186
	s_addc_u32 s1, s1, 0
	s_add_u32 s2, s76, s30
	s_addc_u32 s4, s77, s31
	s_cmpk_eq_i32 s30, 0x300
	s_cselect_b64 vcc, -1, 0
	s_and_b64 s[34:35], vcc, exec
	v_lshl_add_u32 v198, v168, 10, v1
	v_lshl_add_u32 v199, v169, 10, v176
	v_cndmask_b32_e32 v150, v200, v161, vcc
	s_cselect_b32 s37, s17, s1
	s_cselect_b32 s36, s16, s0
	v_cndmask_b32_e32 v172, v158, v163, vcc
	v_cndmask_b32_e32 v201, v160, v198, vcc
	s_cselect_b32 s35, s25, s4
	s_cselect_b32 s34, s75, s2
	v_cndmask_b32_e32 v219, v162, v199, vcc
	v_lshl_add_u64 v[168:169], v[166:167], 0, s[30:31]
	s_add_i32 m0, s42, 0xc000
	ds_read_b128 v[202:205], v196
	ds_read_b128 v[206:209], v196 offset:1024
	ds_read_b128 v[210:213], v196 offset:2048
	ds_read_b128 v[214:217], v196 offset:3072
	ds_read_b128 v[220:223], v196 offset:4096
	ds_read_b128 v[224:227], v196 offset:5120
	ds_read_b128 v[228:231], v196 offset:6144
	ds_read_b128 v[232:235], v196 offset:7168
	global_load_lds_dwordx4 v[168:169], off
	v_lshl_add_u64 v[168:169], v[164:165], 0, s[30:31]
	s_add_i32 m0, s42, 0xe000
	s_nop 0
	global_load_lds_dwordx4 v[168:169], off
	ds_read_b128 v[236:239], v180
	ds_read_b128 v[240:243], v187
	ds_read_b128 v[244:247], v188
	ds_read_b128 v[248:251], v189
	s_waitcnt lgkmcnt(0)
	s_barrier
	s_waitcnt lgkmcnt(0)
	s_setprio 1
	s_waitcnt lgkmcnt(0)
	v_mfma_f32_16x16x128_f8f6f4 v[142:145], v[2:9], v[202:209], v[142:145]
	v_mfma_f32_16x16x128_f8f6f4 v[138:141], v[10:17], v[202:209], v[138:141]
	v_mfma_f32_16x16x128_f8f6f4 v[126:129], v[2:9], v[210:217], v[126:129]
	v_mfma_f32_16x16x128_f8f6f4 v[122:125], v[10:17], v[210:217], v[122:125]
	v_mfma_f32_16x16x128_f8f6f4 v[110:113], v[2:9], v[220:227], v[110:113]
	v_mfma_f32_16x16x128_f8f6f4 v[106:109], v[10:17], v[220:227], v[106:109]
	v_mfma_f32_16x16x128_f8f6f4 v[94:97], v[2:9], v[228:235], v[94:97]
	v_mfma_f32_16x16x128_f8f6f4 v[90:93], v[10:17], v[228:235], v[90:93]
	s_setprio 0
	s_waitcnt lgkmcnt(0)
	s_setprio 1
	s_waitcnt lgkmcnt(0)
	v_mfma_f32_16x16x128_f8f6f4 v[134:137], v[236:243], v[202:209], v[134:137]
	v_mfma_f32_16x16x128_f8f6f4 v[130:133], v[244:251], v[202:209], v[130:133]
	v_mfma_f32_16x16x128_f8f6f4 v[118:121], v[236:243], v[210:217], v[118:121]
	v_mfma_f32_16x16x128_f8f6f4 v[114:117], v[244:251], v[210:217], v[114:117]
	v_mfma_f32_16x16x128_f8f6f4 v[102:105], v[236:243], v[220:227], v[102:105]
	v_mfma_f32_16x16x128_f8f6f4 v[98:101], v[244:251], v[220:227], v[98:101]
	v_mfma_f32_16x16x128_f8f6f4 v[86:89], v[236:243], v[228:235], v[86:89]
	v_mfma_f32_16x16x128_f8f6f4 v[82:85], v[244:251], v[228:235], v[82:85]
	s_setprio 0
	s_barrier
	s_mov_b32 m0, s43
	v_lshl_add_u64 v[168:169], s[34:35], 0, v[148:149]
	global_load_lds_dwordx4 v[168:169], off
	v_lshl_add_u64 v[170:171], s[34:35], 0, v[146:147]
	s_mov_b32 m0, s44
	s_nop 0
	global_load_lds_dwordx4 v[170:171], off
	s_mov_b32 m0, s42
	ds_read_b128 v[202:205], v196 offset:16384
	ds_read_b128 v[206:209], v196 offset:17408
	ds_read_b128 v[210:213], v196 offset:18432
	ds_read_b128 v[214:217], v196 offset:19456
	ds_read_b128 v[220:223], v196 offset:20480
	ds_read_b128 v[224:227], v196 offset:21504
	ds_read_b128 v[228:231], v196 offset:22528
	ds_read_b128 v[232:235], v196 offset:23552
	global_load_lds_dwordx4 v150, s[36:37]
	s_mov_b32 m0, s45
	v_mov_b32_e32 v173, v151
	global_load_lds_dwordx4 v172, s[36:37]
	v_lshl_add_u64 v[174:175], s[36:37], 0, v[150:151]
	v_lshl_add_u64 v[172:173], s[36:37], 0, v[172:173]
	s_add_u32 s66, s34, 0x20000
	s_addc_u32 s67, s35, 0
	s_mov_b32 m0, s46
	v_lshl_add_u64 v[254:255], s[66:67], 0, v[148:149]
	global_load_lds_dwordx4 v[254:255], off
	v_lshl_add_u64 v[254:255], s[66:67], 0, v[146:147]
	s_mov_b32 m0, s47
	s_nop 0
	global_load_lds_dwordx4 v[254:255], off
	s_waitcnt vmcnt(6)
	s_waitcnt lgkmcnt(0)
	s_barrier
	s_waitcnt lgkmcnt(0)
	s_setprio 1
	s_waitcnt lgkmcnt(0)
	v_mfma_f32_16x16x128_f8f6f4 v[78:81], v[2:9], v[202:209], v[78:81]
	v_mfma_f32_16x16x128_f8f6f4 v[74:77], v[10:17], v[202:209], v[74:77]
	v_mfma_f32_16x16x128_f8f6f4 v[62:65], v[2:9], v[210:217], v[62:65]
	v_mfma_f32_16x16x128_f8f6f4 v[58:61], v[10:17], v[210:217], v[58:61]
	v_mfma_f32_16x16x128_f8f6f4 v[46:49], v[2:9], v[220:227], v[46:49]
	v_mfma_f32_16x16x128_f8f6f4 v[42:45], v[10:17], v[220:227], v[42:45]
	v_mfma_f32_16x16x128_f8f6f4 v[30:33], v[2:9], v[228:235], v[30:33]
	v_mfma_f32_16x16x128_f8f6f4 v[26:29], v[10:17], v[228:235], v[26:29]
	s_setprio 0
	s_setprio 1
	v_mfma_f32_16x16x128_f8f6f4 v[70:73], v[236:243], v[202:209], v[70:73]
	v_mfma_f32_16x16x128_f8f6f4 v[66:69], v[244:251], v[202:209], v[66:69]
	v_mfma_f32_16x16x128_f8f6f4 v[54:57], v[236:243], v[210:217], v[54:57]
	v_mfma_f32_16x16x128_f8f6f4 v[50:53], v[244:251], v[210:217], v[50:53]
	v_mfma_f32_16x16x128_f8f6f4 v[38:41], v[236:243], v[220:227], v[38:41]
	v_mfma_f32_16x16x128_f8f6f4 v[34:37], v[244:251], v[220:227], v[34:37]
	v_mfma_f32_16x16x128_f8f6f4 v[22:25], v[236:243], v[228:235], v[22:25]
	v_mfma_f32_16x16x128_f8f6f4 v[18:21], v[244:251], v[228:235], v[18:21]
	s_setprio 0
	s_barrier
	ds_read_b128 v[2:5], v181
	ds_read_b128 v[6:9], v190
	ds_read_b128 v[10:13], v191
	ds_read_b128 v[14:17], v192
	s_mov_b32 m0, s48
	ds_read_b128 v[202:205], v196 offset:32768
	ds_read_b128 v[206:209], v196 offset:33792
	ds_read_b128 v[210:213], v196 offset:34816
	ds_read_b128 v[214:217], v196 offset:35840
	ds_read_b128 v[220:223], v196 offset:36864
	ds_read_b128 v[224:227], v196 offset:37888
	ds_read_b128 v[228:231], v196 offset:38912
	ds_read_b128 v[232:235], v196 offset:39936
	global_load_lds_dwordx4 v201, s[36:37]
	s_mov_b32 m0, s49
	s_nop 0
	global_load_lds_dwordx4 v219, s[36:37]
	ds_read_b128 v[236:239], v182
	ds_read_b128 v[240:243], v193
	ds_read_b128 v[244:247], v194
	ds_read_b128 v[248:251], v195
	s_waitcnt lgkmcnt(0)
	s_barrier
	s_waitcnt lgkmcnt(0)
	s_setprio 1
	s_waitcnt lgkmcnt(0)
	v_mfma_f32_16x16x128_f8f6f4 v[142:145], v[2:9], v[202:209], v[142:145]
	v_mfma_f32_16x16x128_f8f6f4 v[138:141], v[10:17], v[202:209], v[138:141]
	v_mfma_f32_16x16x128_f8f6f4 v[126:129], v[2:9], v[210:217], v[126:129]
	v_mfma_f32_16x16x128_f8f6f4 v[122:125], v[10:17], v[210:217], v[122:125]
	v_mfma_f32_16x16x128_f8f6f4 v[110:113], v[2:9], v[220:227], v[110:113]
	v_mfma_f32_16x16x128_f8f6f4 v[106:109], v[10:17], v[220:227], v[106:109]
	v_mfma_f32_16x16x128_f8f6f4 v[94:97], v[2:9], v[228:235], v[94:97]
	v_mfma_f32_16x16x128_f8f6f4 v[90:93], v[10:17], v[228:235], v[90:93]
	s_setprio 0
	s_waitcnt lgkmcnt(0)
	s_setprio 1
	s_waitcnt lgkmcnt(0)
	v_mfma_f32_16x16x128_f8f6f4 v[134:137], v[236:243], v[202:209], v[134:137]
	v_mfma_f32_16x16x128_f8f6f4 v[130:133], v[244:251], v[202:209], v[130:133]
	v_mfma_f32_16x16x128_f8f6f4 v[118:121], v[236:243], v[210:217], v[118:121]
	v_mfma_f32_16x16x128_f8f6f4 v[114:117], v[244:251], v[210:217], v[114:117]
	v_mfma_f32_16x16x128_f8f6f4 v[102:105], v[236:243], v[220:227], v[102:105]
	v_mfma_f32_16x16x128_f8f6f4 v[98:101], v[244:251], v[220:227], v[98:101]
	v_mfma_f32_16x16x128_f8f6f4 v[86:89], v[236:243], v[228:235], v[86:89]
	v_mfma_f32_16x16x128_f8f6f4 v[82:85], v[244:251], v[228:235], v[82:85]
	s_setprio 0
	s_barrier
	s_mov_b32 m0, s53
	v_lshl_add_u64 v[168:169], v[168:169], 0, s[20:21]
	global_load_lds_dwordx4 v[168:169], off
	v_lshl_add_u64 v[168:169], v[170:171], 0, s[20:21]
	s_mov_b32 m0, s55
	s_nop 0
	global_load_lds_dwordx4 v[168:169], off
	s_mov_b32 m0, s64
	v_lshl_add_u64 v[168:169], v[174:175], 0, s[20:21]
	ds_read_b128 v[202:205], v196 offset:49152
	ds_read_b128 v[206:209], v196 offset:50176
	ds_read_b128 v[210:213], v196 offset:51200
	ds_read_b128 v[214:217], v196 offset:52224
	ds_read_b128 v[220:223], v196 offset:53248
	ds_read_b128 v[224:227], v196 offset:54272
	ds_read_b128 v[228:231], v196 offset:55296
	ds_read_b128 v[232:235], v196 offset:56320
	global_load_lds_dwordx4 v[168:169], off
	v_lshl_add_u64 v[168:169], v[172:173], 0, s[20:21]
	s_mov_b32 m0, s65
	s_nop 0
	global_load_lds_dwordx4 v[168:169], off
	s_add_u32 s34, s34, 0x20080
	s_addc_u32 s35, s35, 0
	s_mov_b32 m0, s68
	v_lshl_add_u64 v[254:255], s[34:35], 0, v[148:149]
	global_load_lds_dwordx4 v[254:255], off
	v_lshl_add_u64 v[254:255], s[34:35], 0, v[146:147]
	s_mov_b32 m0, s69
	s_nop 0
	global_load_lds_dwordx4 v[254:255], off
	s_waitcnt vmcnt(6)
	s_waitcnt lgkmcnt(0)
	s_barrier
	s_waitcnt lgkmcnt(0)
	s_setprio 1
	s_waitcnt lgkmcnt(0)
	v_mfma_f32_16x16x128_f8f6f4 v[78:81], v[2:9], v[202:209], v[78:81]
	v_mfma_f32_16x16x128_f8f6f4 v[74:77], v[10:17], v[202:209], v[74:77]
	v_mfma_f32_16x16x128_f8f6f4 v[62:65], v[2:9], v[210:217], v[62:65]
	v_mfma_f32_16x16x128_f8f6f4 v[58:61], v[10:17], v[210:217], v[58:61]
	v_mfma_f32_16x16x128_f8f6f4 v[46:49], v[2:9], v[220:227], v[46:49]
	v_mfma_f32_16x16x128_f8f6f4 v[42:45], v[10:17], v[220:227], v[42:45]
	v_mfma_f32_16x16x128_f8f6f4 v[30:33], v[2:9], v[228:235], v[30:33]
	v_mfma_f32_16x16x128_f8f6f4 v[26:29], v[10:17], v[228:235], v[26:29]
	s_setprio 0
	s_setprio 1
	v_mfma_f32_16x16x128_f8f6f4 v[70:73], v[236:243], v[202:209], v[70:73]
	v_mfma_f32_16x16x128_f8f6f4 v[66:69], v[244:251], v[202:209], v[66:69]
	v_mfma_f32_16x16x128_f8f6f4 v[54:57], v[236:243], v[210:217], v[54:57]
	v_mfma_f32_16x16x128_f8f6f4 v[50:53], v[244:251], v[210:217], v[50:53]
	v_mfma_f32_16x16x128_f8f6f4 v[38:41], v[236:243], v[220:227], v[38:41]
	v_mfma_f32_16x16x128_f8f6f4 v[34:37], v[244:251], v[220:227], v[34:37]
	v_mfma_f32_16x16x128_f8f6f4 v[22:25], v[236:243], v[228:235], v[22:25]
	v_mfma_f32_16x16x128_f8f6f4 v[18:21], v[244:251], v[228:235], v[18:21]
	s_setprio 0
	s_add_i32 s78, s78, 2
	s_add_u32 s30, s30, 0x100
	s_addc_u32 s31, s31, 0
	s_cmp_gt_u32 s78, 5
	s_barrier
	s_cbranch_scc0 .LBB0_2878
	v_mul_f32_e32 v2, 0xbd38aa3b, v142
	v_exp_f32_e32 v4, v2
	v_mul_f32_e32 v5, 0x3d000000, v143
	v_mul_f32_e32 v7, 0xbd38aa3b, v143
	v_exp_f32_e32 v7, v7
	v_add_f32_e32 v4, 1.0, v4
	v_rcp_f32_e32 v4, v4
	v_mul_f32_e32 v10, 0x3d000000, v140
	v_mul_f32_e32 v12, 0x3d000000, v135
	v_mul_f32_e32 v3, v142, v4
	v_add_f32_e32 v4, 1.0, v7
	v_rcp_f32_e32 v4, v4
	v_mul_f32_e32 v3, v138, v3
	v_mul_f32_e32 v3, 0x3b800000, v3
	v_med3_f32 v7, v3, s71, v197
	v_mul_f32_e32 v4, v143, v4
	v_mul_f32_e32 v8, 0xbd38aa3b, v144
	v_exp_f32_e32 v8, v8
	v_mul_f32_e32 v3, v139, v4
	v_mul_f32_e32 v3, 0x3b800000, v3
	v_add_f32_e32 v4, 1.0, v8
	v_mul_f32_e32 v9, 0xbd38aa3b, v145
	v_rcp_f32_e32 v4, v4
	v_exp_f32_e32 v9, v9
	v_med3_f32 v3, v3, s71, v197
	v_cvt_pk_fp8_f32 v7, v7, v3
	v_mul_f32_e32 v4, v144, v4
	v_add_f32_e32 v5, 1.0, v9
	v_rcp_f32_e32 v5, v5
	v_mul_f32_e32 v4, v140, v4
	v_mul_f32_e32 v4, 0x3b800000, v4
	v_mul_f32_e32 v5, v145, v5
	v_mul_f32_e32 v3, v141, v5
	v_mul_f32_e32 v3, 0x3b800000, v3
	v_med3_f32 v4, v4, s71, v197
	v_med3_f32 v3, v3, s71, v197
	v_cvt_pk_fp8_f32 v7, v4, v3 op_sel:[0,0,1]
	v_mul_f32_e32 v3, 0xbd38aa3b, v134
	v_exp_f32_e32 v11, v3
	v_mul_f32_e32 v13, 0xbd38aa3b, v135
	v_exp_f32_e32 v13, v13
	v_add_f32_e32 v11, 1.0, v11
	v_rcp_f32_e32 v11, v11
	s_mul_hi_i32 s0, s28, 0x2e8ba2e9
	s_lshr_b32 s1, s0, 31
	s_lshr_b32 s0, s0, 2
	v_mul_f32_e32 v10, v134, v11
	v_add_f32_e32 v11, 1.0, v13
	v_rcp_f32_e32 v11, v11
	v_mul_f32_e32 v10, v130, v10
	v_mul_f32_e32 v10, 0x3b800000, v10
	v_mul_f32_e32 v11, v135, v11
	v_mul_f32_e32 v14, 0xbd38aa3b, v136
	v_exp_f32_e32 v14, v14
	v_mul_f32_e32 v11, v131, v11
	v_mul_f32_e32 v11, 0x3b800000, v11
	v_med3_f32 v10, v10, s71, v197
	v_add_f32_e32 v13, 1.0, v14
	v_mul_f32_e32 v14, 0x3d000000, v137
	v_mul_f32_e32 v15, 0xbd38aa3b, v137
	v_rcp_f32_e32 v13, v13
	v_exp_f32_e32 v15, v15
	v_med3_f32 v11, v11, s71, v197
	v_mul_f32_e32 v16, 0x3d000000, v132
	v_mul_f32_e32 v12, v136, v13
	v_add_f32_e32 v13, 1.0, v15
	v_rcp_f32_e32 v13, v13
	v_cvt_pk_fp8_f32 v10, v10, v11
	s_add_i32 s0, s0, s1
	v_mul_f32_e32 v13, v137, v13
	v_mul_f32_e32 v12, v132, v12
	v_mul_f32_e32 v11, v133, v13
	s_mul_i32 s0, s0, 22
	v_mul_f32_e32 v12, 0x3b800000, v12
	v_mul_f32_e32 v11, 0x3b800000, v11
	s_sub_i32 s0, s28, s0
	v_med3_f32 v12, v12, s71, v197
	v_med3_f32 v11, v11, s71, v197
	v_lshl_add_u32 v6, s74, 8, v159
	v_lshl_or_b32 v2, s0, 7, v183
	v_mov_b64_e32 v[4:5], s[14:15]
	v_cvt_pk_fp8_f32 v10, v12, v11 op_sel:[0,0,1]
	v_mad_i64_i32 v[8:9], s[30:31], v6, s72, v[4:5]
	v_ashrrev_i32_e32 v3, 31, v2
	v_lshl_add_u64 v[8:9], v[8:9], 0, v[2:3]
	s_nop 15
	s_nop 15
	global_store_dword v[8:9], v7, off
	global_store_dword v[8:9], v10, off offset:64
	v_mul_f32_e32 v12, 0xbd38aa3b, v126
	v_mul_f32_e32 v10, 0xbd38aa3b, v127
	v_exp_f32_e32 v12, v12
	v_exp_f32_e32 v10, v10
	v_mul_f32_e32 v14, 0x3d000000, v124
	v_or_b32_e32 v7, 16, v6
	v_add_f32_e32 v8, 1.0, v12
	v_add_f32_e32 v10, 1.0, v10
	v_rcp_f32_e32 v8, v8
	v_rcp_f32_e32 v10, v10
	v_mul_f32_e32 v16, 0x3d000000, v116
	v_mul_f32_e32 v8, v126, v8
	v_mul_f32_e32 v9, v127, v10
	v_mul_f32_e32 v8, v122, v8
	v_mul_f32_e32 v12, 0xbd38aa3b, v128
	v_exp_f32_e32 v12, v12
	v_mul_f32_e32 v8, 0x3b800000, v8
	v_med3_f32 v11, v8, s71, v197
	v_mul_f32_e32 v8, v123, v9
	v_add_f32_e32 v9, 1.0, v12
	v_mul_f32_e32 v13, 0xbd38aa3b, v129
	v_rcp_f32_e32 v9, v9
	v_exp_f32_e32 v13, v13
	v_mul_f32_e32 v8, 0x3b800000, v8
	v_med3_f32 v8, v8, s71, v197
	v_mul_f32_e32 v9, v128, v9
	v_add_f32_e32 v10, 1.0, v13
	v_rcp_f32_e32 v10, v10
	v_cvt_pk_fp8_f32 v11, v11, v8
	v_mul_f32_e32 v9, v124, v9
	v_mul_f32_e32 v10, v129, v10
	v_mul_f32_e32 v8, v125, v10
	v_mul_f32_e32 v9, 0x3b800000, v9
	v_mul_f32_e32 v8, 0x3b800000, v8
	v_med3_f32 v9, v9, s71, v197
	v_med3_f32 v8, v8, s71, v197
	v_cvt_pk_fp8_f32 v11, v9, v8 op_sel:[0,0,1]
	v_mul_f32_e32 v8, 0xbd38aa3b, v118
	v_exp_f32_e32 v12, v8
	v_mad_i64_i32 v[8:9], s[30:31], v7, s72, v[4:5]
	v_add_f32_e32 v7, 1.0, v12
	v_mul_f32_e32 v12, 0x3d000000, v119
	v_mul_f32_e32 v13, 0xbd38aa3b, v119
	v_rcp_f32_e32 v7, v7
	v_exp_f32_e32 v13, v13
	v_lshl_add_u64 v[8:9], v[8:9], 0, v[2:3]
	s_and_b64 vcc, exec, s[12:13]
	v_mul_f32_e32 v7, v118, v7
	v_add_f32_e32 v10, 1.0, v13
	v_rcp_f32_e32 v10, v10
	v_mul_f32_e32 v7, v114, v7
	v_mul_f32_e32 v7, 0x3b800000, v7
	v_mul_f32_e32 v10, v119, v10
	v_mul_f32_e32 v14, 0xbd38aa3b, v120
	v_exp_f32_e32 v14, v14
	v_mul_f32_e32 v10, v115, v10
	v_mul_f32_e32 v10, 0x3b800000, v10
	v_med3_f32 v7, v7, s71, v197
	v_add_f32_e32 v13, 1.0, v14
	v_mul_f32_e32 v14, 0x3d000000, v121
	v_mul_f32_e32 v15, 0xbd38aa3b, v121
	v_rcp_f32_e32 v13, v13
	v_exp_f32_e32 v15, v15
	v_med3_f32 v10, v10, s71, v197
	v_cvt_pk_fp8_f32 v7, v7, v10
	v_mul_f32_e32 v12, v120, v13
	v_add_f32_e32 v13, 1.0, v15
	v_rcp_f32_e32 v13, v13
	v_mul_f32_e32 v12, v116, v12
	v_mul_f32_e32 v12, 0x3b800000, v12
	v_mul_f32_e32 v13, v121, v13
	v_mul_f32_e32 v10, v117, v13
	v_mul_f32_e32 v10, 0x3b800000, v10
	v_med3_f32 v12, v12, s71, v197
	v_med3_f32 v10, v10, s71, v197
	v_cvt_pk_fp8_f32 v7, v12, v10 op_sel:[0,0,1]
	v_mul_f32_e32 v12, 0xbd38aa3b, v110
	v_exp_f32_e32 v12, v12
	global_store_dword v[8:9], v11, off
	global_store_dword v[8:9], v7, off offset:64
	v_mul_f32_e32 v11, 0xbd38aa3b, v111
	v_add_f32_e32 v8, 1.0, v12
	v_rcp_f32_e32 v8, v8
	v_exp_f32_e32 v11, v11
	v_mul_f32_e32 v14, 0x3d000000, v108
	v_mul_f32_e32 v8, v110, v8
	v_add_f32_e32 v10, 1.0, v11
	v_rcp_f32_e32 v10, v10
	v_mul_f32_e32 v8, v106, v8
	v_mul_f32_e32 v8, 0x3b800000, v8
	v_med3_f32 v11, v8, s71, v197
	v_mul_f32_e32 v9, v111, v10
	v_mul_f32_e32 v12, 0xbd38aa3b, v112
	v_exp_f32_e32 v12, v12
	v_mul_f32_e32 v8, v107, v9
	v_mul_f32_e32 v8, 0x3b800000, v8
	v_add_f32_e32 v9, 1.0, v12
	v_mul_f32_e32 v13, 0xbd38aa3b, v113
	v_rcp_f32_e32 v9, v9
	v_exp_f32_e32 v13, v13
	v_med3_f32 v8, v8, s71, v197
	v_cvt_pk_fp8_f32 v11, v11, v8
	v_mul_f32_e32 v9, v112, v9
	v_add_f32_e32 v10, 1.0, v13
	v_rcp_f32_e32 v10, v10
	v_mul_f32_e32 v9, v108, v9
	v_mul_f32_e32 v9, 0x3b800000, v9
	v_mul_f32_e32 v10, v113, v10
	v_mul_f32_e32 v8, v109, v10
	v_mul_f32_e32 v8, 0x3b800000, v8
	v_med3_f32 v9, v9, s71, v197
	v_med3_f32 v8, v8, s71, v197
	v_cvt_pk_fp8_f32 v11, v9, v8 op_sel:[0,0,1]
	v_mul_f32_e32 v8, 0xbd38aa3b, v102
	v_exp_f32_e32 v12, v8
	v_or_b32_e32 v7, 32, v6
	v_mad_i64_i32 v[8:9], s[30:31], v7, s72, v[4:5]
	v_add_f32_e32 v7, 1.0, v12
	v_mul_f32_e32 v12, 0x3d000000, v103
	v_mul_f32_e32 v13, 0xbd38aa3b, v103
	v_rcp_f32_e32 v7, v7
	v_exp_f32_e32 v13, v13
	v_mul_f32_e32 v16, 0x3d000000, v100
	v_mul_f32_e32 v7, v102, v7
	v_add_f32_e32 v10, 1.0, v13
	v_rcp_f32_e32 v10, v10
	v_mul_f32_e32 v7, v98, v7
	v_mul_f32_e32 v7, 0x3b800000, v7
	v_mul_f32_e32 v10, v103, v10
	v_mul_f32_e32 v14, 0xbd38aa3b, v104
	v_exp_f32_e32 v14, v14
	v_mul_f32_e32 v10, v99, v10
	v_mul_f32_e32 v10, 0x3b800000, v10
	v_med3_f32 v7, v7, s71, v197
	v_add_f32_e32 v13, 1.0, v14
	v_mul_f32_e32 v14, 0x3d000000, v105
	v_mul_f32_e32 v15, 0xbd38aa3b, v105
	v_rcp_f32_e32 v13, v13
	v_exp_f32_e32 v15, v15
	v_med3_f32 v10, v10, s71, v197
	v_cvt_pk_fp8_f32 v7, v7, v10
	v_mul_f32_e32 v12, v104, v13
	v_add_f32_e32 v13, 1.0, v15
	v_rcp_f32_e32 v13, v13
	v_mul_f32_e32 v12, v100, v12
	v_mul_f32_e32 v12, 0x3b800000, v12
	v_mul_f32_e32 v13, v105, v13
	v_mul_f32_e32 v10, v101, v13
	v_mul_f32_e32 v10, 0x3b800000, v10
	v_med3_f32 v12, v12, s71, v197
	v_med3_f32 v10, v10, s71, v197
	v_cvt_pk_fp8_f32 v7, v12, v10 op_sel:[0,0,1]
	v_mul_f32_e32 v12, 0xbd38aa3b, v94
	v_exp_f32_e32 v12, v12
	v_lshl_add_u64 v[8:9], v[8:9], 0, v[2:3]
	global_store_dword v[8:9], v11, off
	global_store_dword v[8:9], v7, off offset:64
	v_add_f32_e32 v8, 1.0, v12
	v_mul_f32_e32 v11, 0xbd38aa3b, v95
	v_rcp_f32_e32 v8, v8
	v_exp_f32_e32 v11, v11
	v_mul_f32_e32 v14, 0x3d000000, v92
	v_mul_f32_e32 v8, v94, v8
	v_add_f32_e32 v10, 1.0, v11
	v_rcp_f32_e32 v10, v10
	v_mul_f32_e32 v8, v90, v8
	v_mul_f32_e32 v8, 0x3b800000, v8
	v_med3_f32 v11, v8, s71, v197
	v_mul_f32_e32 v9, v95, v10
	v_mul_f32_e32 v12, 0xbd38aa3b, v96
	v_exp_f32_e32 v12, v12
	v_mul_f32_e32 v8, v91, v9
	v_mul_f32_e32 v8, 0x3b800000, v8
	v_add_f32_e32 v9, 1.0, v12
	v_mul_f32_e32 v13, 0xbd38aa3b, v97
	v_rcp_f32_e32 v9, v9
	v_exp_f32_e32 v13, v13
	v_med3_f32 v8, v8, s71, v197
	v_cvt_pk_fp8_f32 v11, v11, v8
	v_mul_f32_e32 v9, v96, v9
	v_add_f32_e32 v10, 1.0, v13
	v_rcp_f32_e32 v10, v10
	v_mul_f32_e32 v9, v92, v9
	v_mul_f32_e32 v9, 0x3b800000, v9
	v_mul_f32_e32 v10, v97, v10
	v_mul_f32_e32 v8, v93, v10
	v_mul_f32_e32 v8, 0x3b800000, v8
	v_med3_f32 v9, v9, s71, v197
	v_med3_f32 v8, v8, s71, v197
	v_cvt_pk_fp8_f32 v11, v9, v8 op_sel:[0,0,1]
	v_mul_f32_e32 v8, 0xbd38aa3b, v86
	v_exp_f32_e32 v12, v8
	v_or_b32_e32 v7, 48, v6
	v_mad_i64_i32 v[8:9], s[30:31], v7, s72, v[4:5]
	v_add_f32_e32 v7, 1.0, v12
	v_mul_f32_e32 v12, 0x3d000000, v87
	v_mul_f32_e32 v13, 0xbd38aa3b, v87
	v_rcp_f32_e32 v7, v7
	v_exp_f32_e32 v13, v13
	v_mul_f32_e32 v16, 0x3d000000, v84
	v_mul_f32_e32 v7, v86, v7
	v_add_f32_e32 v10, 1.0, v13
	v_rcp_f32_e32 v10, v10
	v_mul_f32_e32 v7, v82, v7
	v_mul_f32_e32 v7, 0x3b800000, v7
	v_mul_f32_e32 v10, v87, v10
	v_mul_f32_e32 v14, 0xbd38aa3b, v88
	v_exp_f32_e32 v14, v14
	v_mul_f32_e32 v10, v83, v10
	v_mul_f32_e32 v10, 0x3b800000, v10
	v_med3_f32 v7, v7, s71, v197
	v_add_f32_e32 v13, 1.0, v14
	v_mul_f32_e32 v14, 0x3d000000, v89
	v_mul_f32_e32 v15, 0xbd38aa3b, v89
	v_rcp_f32_e32 v13, v13
	v_exp_f32_e32 v15, v15
	v_med3_f32 v10, v10, s71, v197
	v_cvt_pk_fp8_f32 v7, v7, v10
	v_mul_f32_e32 v12, v88, v13
	v_add_f32_e32 v13, 1.0, v15
	v_rcp_f32_e32 v13, v13
	v_mul_f32_e32 v12, v84, v12
	v_mul_f32_e32 v12, 0x3b800000, v12
	v_mul_f32_e32 v13, v89, v13
	v_mul_f32_e32 v10, v85, v13
	v_mul_f32_e32 v10, 0x3b800000, v10
	v_med3_f32 v12, v12, s71, v197
	v_med3_f32 v10, v10, s71, v197
	v_cvt_pk_fp8_f32 v7, v12, v10 op_sel:[0,0,1]
	v_mul_f32_e32 v12, 0xbd38aa3b, v78
	v_exp_f32_e32 v12, v12
	v_lshl_add_u64 v[8:9], v[8:9], 0, v[2:3]
	global_store_dword v[8:9], v11, off
	global_store_dword v[8:9], v7, off offset:64
	v_add_f32_e32 v8, 1.0, v12
	v_mul_f32_e32 v11, 0xbd38aa3b, v79
	v_rcp_f32_e32 v8, v8
	v_exp_f32_e32 v11, v11
	v_mul_f32_e32 v14, 0x3d000000, v76
	v_mul_f32_e32 v8, v78, v8
	v_add_f32_e32 v10, 1.0, v11
	v_rcp_f32_e32 v10, v10
	v_mul_f32_e32 v8, v74, v8
	v_mul_f32_e32 v8, 0x3b800000, v8
	v_med3_f32 v11, v8, s71, v197
	v_mul_f32_e32 v9, v79, v10
	v_mul_f32_e32 v12, 0xbd38aa3b, v80
	v_exp_f32_e32 v12, v12
	v_mul_f32_e32 v8, v75, v9
	v_mul_f32_e32 v8, 0x3b800000, v8
	v_add_f32_e32 v9, 1.0, v12
	v_mul_f32_e32 v13, 0xbd38aa3b, v81
	v_rcp_f32_e32 v9, v9
	v_exp_f32_e32 v13, v13
	v_med3_f32 v8, v8, s71, v197
	v_cvt_pk_fp8_f32 v11, v11, v8
	v_mul_f32_e32 v9, v80, v9
	v_add_f32_e32 v10, 1.0, v13
	v_rcp_f32_e32 v10, v10
	v_mul_f32_e32 v9, v76, v9
	v_mul_f32_e32 v9, 0x3b800000, v9
	v_mul_f32_e32 v10, v81, v10
	v_mul_f32_e32 v8, v77, v10
	v_mul_f32_e32 v8, 0x3b800000, v8
	v_med3_f32 v9, v9, s71, v197
	v_med3_f32 v8, v8, s71, v197
	v_cvt_pk_fp8_f32 v11, v9, v8 op_sel:[0,0,1]
	v_mul_f32_e32 v8, 0xbd38aa3b, v70
	v_exp_f32_e32 v12, v8
	v_add_u32_e32 v7, 0x80, v6
	v_mad_i64_i32 v[8:9], s[30:31], v7, s72, v[4:5]
	v_add_f32_e32 v7, 1.0, v12
	v_mul_f32_e32 v12, 0x3d000000, v71
	v_mul_f32_e32 v13, 0xbd38aa3b, v71
	v_rcp_f32_e32 v7, v7
	v_exp_f32_e32 v13, v13
	v_mul_f32_e32 v16, 0x3d000000, v68
	v_mul_f32_e32 v7, v70, v7
	v_add_f32_e32 v10, 1.0, v13
	v_rcp_f32_e32 v10, v10
	v_mul_f32_e32 v7, v66, v7
	v_mul_f32_e32 v7, 0x3b800000, v7
	v_mul_f32_e32 v10, v71, v10
	v_mul_f32_e32 v14, 0xbd38aa3b, v72
	v_exp_f32_e32 v14, v14
	v_mul_f32_e32 v10, v67, v10
	v_mul_f32_e32 v10, 0x3b800000, v10
	v_med3_f32 v7, v7, s71, v197
	v_add_f32_e32 v13, 1.0, v14
	v_mul_f32_e32 v14, 0x3d000000, v73
	v_mul_f32_e32 v15, 0xbd38aa3b, v73
	v_rcp_f32_e32 v13, v13
	v_exp_f32_e32 v15, v15
	v_med3_f32 v10, v10, s71, v197
	v_cvt_pk_fp8_f32 v7, v7, v10
	v_mul_f32_e32 v12, v72, v13
	v_add_f32_e32 v13, 1.0, v15
	v_rcp_f32_e32 v13, v13
	v_mul_f32_e32 v12, v68, v12
	v_mul_f32_e32 v12, 0x3b800000, v12
	v_mul_f32_e32 v13, v73, v13
	v_mul_f32_e32 v10, v69, v13
	v_mul_f32_e32 v10, 0x3b800000, v10
	v_med3_f32 v12, v12, s71, v197
	v_med3_f32 v10, v10, s71, v197
	v_cvt_pk_fp8_f32 v7, v12, v10 op_sel:[0,0,1]
	v_mul_f32_e32 v12, 0xbd38aa3b, v62
	v_exp_f32_e32 v12, v12
	v_lshl_add_u64 v[8:9], v[8:9], 0, v[2:3]
	global_store_dword v[8:9], v11, off
	global_store_dword v[8:9], v7, off offset:64
	v_add_f32_e32 v8, 1.0, v12
	v_mul_f32_e32 v11, 0xbd38aa3b, v63
	v_rcp_f32_e32 v8, v8
	v_exp_f32_e32 v11, v11
	v_mul_f32_e32 v14, 0x3d000000, v60
	v_mul_f32_e32 v8, v62, v8
	v_add_f32_e32 v10, 1.0, v11
	v_rcp_f32_e32 v10, v10
	v_mul_f32_e32 v8, v58, v8
	v_mul_f32_e32 v8, 0x3b800000, v8
	v_med3_f32 v11, v8, s71, v197
	v_mul_f32_e32 v9, v63, v10
	v_mul_f32_e32 v12, 0xbd38aa3b, v64
	v_exp_f32_e32 v12, v12
	v_mul_f32_e32 v8, v59, v9
	v_mul_f32_e32 v8, 0x3b800000, v8
	v_add_f32_e32 v9, 1.0, v12
	v_mul_f32_e32 v13, 0xbd38aa3b, v65
	v_rcp_f32_e32 v9, v9
	v_exp_f32_e32 v13, v13
	v_med3_f32 v8, v8, s71, v197
	v_cvt_pk_fp8_f32 v11, v11, v8
	v_mul_f32_e32 v9, v64, v9
	v_add_f32_e32 v10, 1.0, v13
	v_rcp_f32_e32 v10, v10
	v_mul_f32_e32 v9, v60, v9
	v_mul_f32_e32 v9, 0x3b800000, v9
	v_mul_f32_e32 v10, v65, v10
	v_mul_f32_e32 v8, v61, v10
	v_mul_f32_e32 v8, 0x3b800000, v8
	v_med3_f32 v9, v9, s71, v197
	v_med3_f32 v8, v8, s71, v197
	v_cvt_pk_fp8_f32 v11, v9, v8 op_sel:[0,0,1]
	v_mul_f32_e32 v8, 0xbd38aa3b, v54
	v_exp_f32_e32 v12, v8
	v_add_u32_e32 v7, 0x90, v6
	v_mad_i64_i32 v[8:9], s[30:31], v7, s72, v[4:5]
	v_add_f32_e32 v7, 1.0, v12
	v_mul_f32_e32 v12, 0x3d000000, v55
	v_mul_f32_e32 v13, 0xbd38aa3b, v55
	v_rcp_f32_e32 v7, v7
	v_exp_f32_e32 v13, v13
	v_mul_f32_e32 v16, 0x3d000000, v52
	v_mul_f32_e32 v7, v54, v7
	v_add_f32_e32 v10, 1.0, v13
	v_rcp_f32_e32 v10, v10
	v_mul_f32_e32 v7, v50, v7
	v_mul_f32_e32 v7, 0x3b800000, v7
	v_mul_f32_e32 v10, v55, v10
	v_mul_f32_e32 v14, 0xbd38aa3b, v56
	v_exp_f32_e32 v14, v14
	v_mul_f32_e32 v10, v51, v10
	v_mul_f32_e32 v10, 0x3b800000, v10
	v_med3_f32 v7, v7, s71, v197
	v_add_f32_e32 v13, 1.0, v14
	v_mul_f32_e32 v14, 0x3d000000, v57
	v_mul_f32_e32 v15, 0xbd38aa3b, v57
	v_rcp_f32_e32 v13, v13
	v_exp_f32_e32 v15, v15
	v_med3_f32 v10, v10, s71, v197
	v_cvt_pk_fp8_f32 v7, v7, v10
	v_mul_f32_e32 v12, v56, v13
	v_add_f32_e32 v13, 1.0, v15
	v_rcp_f32_e32 v13, v13
	v_mul_f32_e32 v12, v52, v12
	v_mul_f32_e32 v12, 0x3b800000, v12
	v_mul_f32_e32 v13, v57, v13
	v_mul_f32_e32 v10, v53, v13
	v_mul_f32_e32 v10, 0x3b800000, v10
	v_med3_f32 v12, v12, s71, v197
	v_med3_f32 v10, v10, s71, v197
	v_cvt_pk_fp8_f32 v7, v12, v10 op_sel:[0,0,1]
	v_mul_f32_e32 v12, 0xbd38aa3b, v46
	v_exp_f32_e32 v12, v12
	v_lshl_add_u64 v[8:9], v[8:9], 0, v[2:3]
	global_store_dword v[8:9], v11, off
	global_store_dword v[8:9], v7, off offset:64
	v_add_f32_e32 v8, 1.0, v12
	v_mul_f32_e32 v11, 0xbd38aa3b, v47
	v_rcp_f32_e32 v8, v8
	v_exp_f32_e32 v11, v11
	v_mul_f32_e32 v14, 0x3d000000, v44
	v_mul_f32_e32 v8, v46, v8
	v_add_f32_e32 v10, 1.0, v11
	v_rcp_f32_e32 v10, v10
	v_mul_f32_e32 v8, v42, v8
	v_mul_f32_e32 v8, 0x3b800000, v8
	v_med3_f32 v11, v8, s71, v197
	v_mul_f32_e32 v9, v47, v10
	v_mul_f32_e32 v12, 0xbd38aa3b, v48
	v_exp_f32_e32 v12, v12
	v_mul_f32_e32 v8, v43, v9
	v_mul_f32_e32 v8, 0x3b800000, v8
	v_add_f32_e32 v9, 1.0, v12
	v_mul_f32_e32 v13, 0xbd38aa3b, v49
	v_rcp_f32_e32 v9, v9
	v_exp_f32_e32 v13, v13
	v_med3_f32 v8, v8, s71, v197
	v_cvt_pk_fp8_f32 v11, v11, v8
	v_mul_f32_e32 v9, v48, v9
	v_add_f32_e32 v10, 1.0, v13
	v_rcp_f32_e32 v10, v10
	v_mul_f32_e32 v9, v44, v9
	v_mul_f32_e32 v9, 0x3b800000, v9
	v_mul_f32_e32 v10, v49, v10
	v_mul_f32_e32 v8, v45, v10
	v_mul_f32_e32 v8, 0x3b800000, v8
	v_med3_f32 v9, v9, s71, v197
	v_med3_f32 v8, v8, s71, v197
	v_cvt_pk_fp8_f32 v11, v9, v8 op_sel:[0,0,1]
	v_mul_f32_e32 v8, 0xbd38aa3b, v38
	v_exp_f32_e32 v12, v8
	v_add_u32_e32 v7, 0xa0, v6
	v_mad_i64_i32 v[8:9], s[30:31], v7, s72, v[4:5]
	v_add_f32_e32 v7, 1.0, v12
	v_mul_f32_e32 v12, 0x3d000000, v39
	v_mul_f32_e32 v13, 0xbd38aa3b, v39
	v_rcp_f32_e32 v7, v7
	v_exp_f32_e32 v13, v13
	v_mul_f32_e32 v7, v38, v7
	v_add_f32_e32 v10, 1.0, v13
	v_rcp_f32_e32 v10, v10
	v_mul_f32_e32 v7, v34, v7
	v_mul_f32_e32 v7, 0x3b800000, v7
	v_mul_f32_e32 v10, v39, v10
	v_mul_f32_e32 v14, 0xbd38aa3b, v40
	v_exp_f32_e32 v14, v14
	v_mul_f32_e32 v10, v35, v10
	v_mul_f32_e32 v10, 0x3b800000, v10
	v_med3_f32 v7, v7, s71, v197
	v_add_f32_e32 v13, 1.0, v14
	v_mul_f32_e32 v14, 0x3d000000, v41
	v_mul_f32_e32 v15, 0xbd38aa3b, v41
	v_rcp_f32_e32 v13, v13
	v_exp_f32_e32 v15, v15
	v_med3_f32 v10, v10, s71, v197
	v_cvt_pk_fp8_f32 v7, v7, v10
	v_mul_f32_e32 v12, v40, v13
	v_add_f32_e32 v13, 1.0, v15
	v_rcp_f32_e32 v13, v13
	v_mul_f32_e32 v12, v36, v12
	v_mul_f32_e32 v12, 0x3b800000, v12
	v_mul_f32_e32 v13, v41, v13
	v_mul_f32_e32 v10, v37, v13
	v_mul_f32_e32 v10, 0x3b800000, v10
	v_med3_f32 v12, v12, s71, v197
	v_med3_f32 v10, v10, s71, v197
	v_cvt_pk_fp8_f32 v7, v12, v10 op_sel:[0,0,1]
	v_lshl_add_u64 v[8:9], v[8:9], 0, v[2:3]
	v_mul_f32_e32 v10, 0x3d000000, v30
	global_store_dword v[8:9], v11, off
	global_store_dword v[8:9], v7, off offset:64
	v_mul_f32_e32 v12, 0xbd38aa3b, v30
	v_mul_f32_e32 v9, 0xbd38aa3b, v31
	v_exp_f32_e32 v12, v12
	v_exp_f32_e32 v9, v9
	v_add_f32_e32 v7, 1.0, v12
	v_add_f32_e32 v9, 1.0, v9
	v_rcp_f32_e32 v7, v7
	v_rcp_f32_e32 v9, v9
	v_add_u32_e32 v6, 0xb0, v6
	v_mul_f32_e32 v7, v30, v7
	v_mul_f32_e32 v8, v31, v9
	v_mul_f32_e32 v7, v26, v7
	v_mul_f32_e32 v11, 0xbd38aa3b, v32
	v_exp_f32_e32 v11, v11
	v_mul_f32_e32 v8, v27, v8
	v_mul_f32_e32 v7, 0x3b800000, v7
	v_add_f32_e32 v10, 1.0, v11
	v_mul_f32_e32 v12, 0xbd38aa3b, v33
	v_rcp_f32_e32 v10, v10
	v_exp_f32_e32 v12, v12
	v_mul_f32_e32 v8, 0x3b800000, v8
	v_med3_f32 v7, v7, s71, v197
	v_mul_f32_e32 v9, v32, v10
	v_add_f32_e32 v10, 1.0, v12
	v_rcp_f32_e32 v10, v10
	v_med3_f32 v8, v8, s71, v197
	v_cvt_pk_fp8_f32 v7, v7, v8
	v_mul_f32_e32 v12, 0x3d000000, v29
	v_mul_f32_e32 v10, v33, v10
	v_mul_f32_e32 v11, 0xbd38aa3b, v22
	v_mul_f32_e32 v9, v28, v9
	v_mul_f32_e32 v10, v29, v10
	v_exp_f32_e32 v11, v11
	v_mul_f32_e32 v9, 0x3b800000, v9
	v_mul_f32_e32 v10, 0x3b800000, v10
	v_med3_f32 v9, v9, s71, v197
	v_med3_f32 v10, v10, s71, v197
	v_cvt_pk_fp8_f32 v7, v9, v10 op_sel:[0,0,1]
	v_mul_f32_e32 v10, 0x3d000000, v23
	v_add_f32_e32 v9, 1.0, v11
	v_mul_f32_e32 v11, 0xbd38aa3b, v23
	v_rcp_f32_e32 v9, v9
	v_exp_f32_e32 v11, v11
	v_mad_i64_i32 v[4:5], s[30:31], v6, s72, v[4:5]
	v_mul_f32_e32 v8, v22, v9
	v_add_f32_e32 v9, 1.0, v11
	v_rcp_f32_e32 v9, v9
	v_mul_f32_e32 v8, v18, v8
	v_mul_f32_e32 v8, 0x3b800000, v8
	v_mul_f32_e32 v9, v23, v9
	v_mul_f32_e32 v12, 0xbd38aa3b, v24
	v_exp_f32_e32 v12, v12
	v_mul_f32_e32 v9, v19, v9
	v_mul_f32_e32 v9, 0x3b800000, v9
	v_med3_f32 v8, v8, s71, v197
	v_add_f32_e32 v11, 1.0, v12
	v_mul_f32_e32 v13, 0xbd38aa3b, v25
	v_rcp_f32_e32 v11, v11
	v_exp_f32_e32 v13, v13
	v_med3_f32 v9, v9, s71, v197
	v_cvt_pk_fp8_f32 v8, v8, v9
	v_mul_f32_e32 v10, v24, v11
	v_add_f32_e32 v11, 1.0, v13
	v_rcp_f32_e32 v11, v11
	v_mul_f32_e32 v10, v20, v10
	v_mul_f32_e32 v10, 0x3b800000, v10
	v_mul_f32_e32 v11, v25, v11
	v_mul_f32_e32 v9, v21, v11
	v_mul_f32_e32 v9, 0x3b800000, v9
	v_med3_f32 v10, v10, s71, v197
	v_med3_f32 v9, v9, s71, v197
	v_cvt_pk_fp8_f32 v8, v10, v9 op_sel:[0,0,1]
	v_lshl_add_u64 v[2:3], v[4:5], 0, v[2:3]
	v_mov_b32_e32 v200, v161
	v_mov_b32_e32 v158, v163
	v_mov_b32_e32 v160, v198
	v_mov_b32_e32 v162, v199
	s_mov_b32 s28, s24
	s_mov_b32 s74, s73
	s_mov_b64 s[30:31], s[26:27]
	global_store_dword v[2:3], v7, off
	global_store_dword v[2:3], v8, off offset:64
	s_cbranch_vccz .LBB0_2875
	s_waitcnt vmcnt(0)
	s_cmpk_gt_u32 s39, 0xff
	s_cbranch_scc1 .LBB0_2882
	s_barrier

.LBB0_3111:
	s_lshl_b32 s1, s14, 5
	s_add_i32 s69, s47, 0x18000
	s_mov_b64 s[28:29], 0x80
	s_and_b32 s1, s1, 0x60
	v_lshl_add_u64 v[8:9], v[8:9], 0, s[28:29]
	s_mov_b32 m0, s69
	s_add_i32 s70, s47, 0x1a000
	s_lshl_b32 s0, s13, 13
	s_lshl_b32 s2, s1, 7
	s_waitcnt vmcnt(0)
	s_barrier
	global_load_lds_dwordx4 v[8:9], off
	v_lshl_add_u64 v[6:7], v[6:7], 0, s[28:29]
	s_mov_b32 m0, s70
	s_add_i32 s71, s47, 0x8000
	s_add_i32 s72, s47, 0xa000
	global_load_lds_dwordx4 v[6:7], off
	v_lshl_add_u64 v[4:5], v[4:5], 0, s[28:29]
	s_mov_b32 m0, s71
	s_add_u32 s14, s40, 0x58080
	global_load_lds_dwordx4 v[4:5], off
	v_lshl_add_u64 v[2:3], v[2:3], 0, s[28:29]
	s_mov_b32 m0, s72
	s_addc_u32 s15, s41, 0
	s_add_i32 s73, s47, 0x1c000
	global_load_lds_dwordx4 v[2:3], off
	v_lshl_add_u64 v[2:3], s[14:15], 0, v[146:147]
	s_mov_b32 m0, s73
	s_add_i32 s74, s47, 0x1e000
	global_load_lds_dwordx4 v[2:3], off
	v_lshl_add_u64 v[2:3], s[14:15], 0, v[148:149]
	s_mov_b32 m0, s74
	v_lshlrev_b32_e32 v5, 2, v10
	global_load_lds_dwordx4 v[2:3], off
	v_and_b32_e32 v2, 15, v10
	v_bfe_u32 v3, v10, 4, 2
	v_lshl_or_b32 v166, s13, 6, v2
	v_lshlrev_b32_e32 v4, 4, v3
	v_lshlrev_b32_e32 v2, 6, v2
	v_and_b32_e32 v5, 32, v5
	v_bitop3_b32 v2, v2, v5, v4 bitop3:0x36
	s_add_i32 s2, s2, 0
	v_add_u32_e32 v4, s2, v2
	v_add_u32_e32 v5, 0, v2
	v_lshl_or_b32 v183, v3, 2, s1
	v_lshrrev_b32_e32 v3, 1, v15
	v_mul_lo_u32 v2, v17, s12
	s_movk_i32 s1, 0x5800
	v_mad_u64_u32 v[2:3], s[16:17], v3, s1, v[2:3]
	v_or_b32_e32 v2, v2, v16
	s_mov_b64 s[14:15], 0x58080
	v_add_lshl_u32 v2, v2, v18, 1
	v_mov_b32_e32 v3, v147
	v_lshl_add_u64 v[150:151], v[2:3], 0, s[14:15]
	v_lshrrev_b32_e32 v3, 1, v11
	v_mul_lo_u32 v2, v12, s12
	v_mad_u64_u32 v[2:3], s[12:13], v3, s1, v[2:3]
	s_waitcnt vmcnt(6)
	v_or_b32_e32 v2, v2, v13
	v_readlane_b32 s2, v252, 8
	v_add_lshl_u32 v2, v2, v14, 1
	v_mov_b32_e32 v3, v147
	v_add_u32_e32 v167, 0x10000, v4
	v_add_u32_e32 v168, 0x14000, v4
	v_add_u32_e32 v169, 0x18000, v4
	v_add_u32_e32 v170, 0x1c000, v4
	v_add_u32_e32 v171, 0x10400, v4
	v_add_u32_e32 v172, 0x10800, v4
	v_add_u32_e32 v173, 0x10c00, v4
	v_add_u32_e32 v174, 0x14400, v4
	v_add_u32_e32 v175, 0x14800, v4
	v_add_u32_e32 v176, 0x14c00, v4
	v_add_u32_e32 v177, 0x18400, v4
	v_add_u32_e32 v178, 0x18800, v4
	v_add_u32_e32 v179, 0x18c00, v4
	v_add_u32_e32 v180, 0x1c400, v4
	v_add_u32_e32 v181, 0x1c800, v4
	v_add_u32_e32 v182, 0x1cc00, v4
	s_ashr_i32 s75, s2, 31
	v_lshl_add_u64 v[152:153], v[2:3], 0, s[14:15]
	v_mov_b64_e32 v[154:155], 0x400
	v_mov_b64_e32 v[156:157], 0x3ff
	v_add_u32_e32 v184, s0, v5
	s_mov_b64 s[30:31], 0x40000
	s_mov_b32 s76, 0x40000
	s_mov_b64 s[34:35], 0x48000
	s_mov_b32 s77, 0x48000
	s_mov_b64 s[36:37], 0x50000
	s_mov_b32 s78, 0x50000
	s_mov_b32 s79, 0x58000
	s_barrier

.LBB0_3123:
	ds_read_b128 v[2:5], v167
	ds_read_b128 v[6:9], v171
	ds_read_b128 v[10:13], v172
	ds_read_b128 v[14:17], v173
	s_add_u32 s40, s38, 0x100
	s_addc_u32 s41, s39, 0
	s_cmp_eq_u32 s86, 18
	s_cselect_b32 s45, s15, s41
	s_cselect_b32 s44, s14, s40
	s_cselect_b32 s43, s17, s85
	s_cselect_b32 s42, s16, s84
	v_lshl_add_u64 v[158:159], s[38:39], 0, v[152:153]
	s_add_i32 m0, s47, 0xc000
	ds_read_b128 v[186:189], v184
	ds_read_b128 v[190:193], v184 offset:1024
	ds_read_b128 v[194:197], v184 offset:2048
	ds_read_b128 v[198:201], v184 offset:3072
	ds_read_b128 v[202:205], v184 offset:4096
	ds_read_b128 v[206:209], v184 offset:5120
	ds_read_b128 v[210:213], v184 offset:6144
	ds_read_b128 v[214:217], v184 offset:7168
	global_load_lds_dwordx4 v[158:159], off
	v_lshl_add_u64 v[158:159], s[38:39], 0, v[150:151]
	s_add_i32 m0, s47, 0xe000
	s_nop 0
	global_load_lds_dwordx4 v[158:159], off
	ds_read_b128 v[220:223], v168
	ds_read_b128 v[224:227], v174
	ds_read_b128 v[228:231], v175
	ds_read_b128 v[232:235], v176
	s_waitcnt lgkmcnt(0)
	s_barrier
	s_waitcnt lgkmcnt(0)
	s_setprio 1
	s_waitcnt lgkmcnt(0)
	v_mfma_f32_16x16x128_f8f6f4 v[142:145], v[2:9], v[186:193], v[142:145]
	v_mfma_f32_16x16x128_f8f6f4 v[138:141], v[10:17], v[186:193], v[138:141]
	v_mfma_f32_16x16x128_f8f6f4 v[134:137], v[2:9], v[194:201], v[134:137]
	v_mfma_f32_16x16x128_f8f6f4 v[130:133], v[10:17], v[194:201], v[130:133]
	v_mfma_f32_16x16x128_f8f6f4 v[110:113], v[2:9], v[202:209], v[110:113]
	v_mfma_f32_16x16x128_f8f6f4 v[106:109], v[10:17], v[202:209], v[106:109]
	v_mfma_f32_16x16x128_f8f6f4 v[102:105], v[2:9], v[210:217], v[102:105]
	v_mfma_f32_16x16x128_f8f6f4 v[98:101], v[10:17], v[210:217], v[98:101]
	s_setprio 0
	s_waitcnt lgkmcnt(0)
	s_setprio 1
	s_waitcnt lgkmcnt(0)
	v_mfma_f32_16x16x128_f8f6f4 v[126:129], v[220:227], v[186:193], v[126:129]
	v_mfma_f32_16x16x128_f8f6f4 v[122:125], v[228:235], v[186:193], v[122:125]
	v_mfma_f32_16x16x128_f8f6f4 v[118:121], v[220:227], v[194:201], v[118:121]
	v_mfma_f32_16x16x128_f8f6f4 v[114:117], v[228:235], v[194:201], v[114:117]
	v_mfma_f32_16x16x128_f8f6f4 v[94:97], v[220:227], v[202:209], v[94:97]
	v_mfma_f32_16x16x128_f8f6f4 v[90:93], v[228:235], v[202:209], v[90:93]
	v_mfma_f32_16x16x128_f8f6f4 v[86:89], v[220:227], v[210:217], v[86:89]
	v_mfma_f32_16x16x128_f8f6f4 v[82:85], v[228:235], v[210:217], v[82:85]
	s_setprio 0
	s_barrier
	s_mov_b32 m0, s48
	v_lshl_add_u64 v[158:159], s[42:43], 0, v[146:147]
	global_load_lds_dwordx4 v[158:159], off
	v_lshl_add_u64 v[160:161], s[42:43], 0, v[148:149]
	s_mov_b32 m0, s49
	s_nop 0
	global_load_lds_dwordx4 v[160:161], off
	s_mov_b32 m0, s47
	v_lshl_add_u64 v[162:163], s[44:45], 0, v[146:147]
	ds_read_b128 v[186:189], v184 offset:16384
	ds_read_b128 v[190:193], v184 offset:17408
	ds_read_b128 v[194:197], v184 offset:18432
	ds_read_b128 v[198:201], v184 offset:19456
	ds_read_b128 v[202:205], v184 offset:20480
	ds_read_b128 v[206:209], v184 offset:21504
	ds_read_b128 v[210:213], v184 offset:22528
	ds_read_b128 v[214:217], v184 offset:23552
	global_load_lds_dwordx4 v[162:163], off
	v_lshl_add_u64 v[164:165], s[44:45], 0, v[148:149]
	s_mov_b32 m0, s52
	s_nop 0
	global_load_lds_dwordx4 v[164:165], off
	s_add_u32 s38, s42, 0x58000
	s_addc_u32 s39, s43, 0
	s_mov_b32 m0, s53
	v_lshl_add_u64 v[254:255], s[38:39], 0, v[146:147]
	global_load_lds_dwordx4 v[254:255], off
	v_lshl_add_u64 v[254:255], s[38:39], 0, v[148:149]
	s_mov_b32 m0, s55
	s_nop 0
	global_load_lds_dwordx4 v[254:255], off
	s_waitcnt vmcnt(6)
	s_waitcnt lgkmcnt(0)
	s_barrier
	s_waitcnt lgkmcnt(0)
	s_setprio 1
	s_waitcnt lgkmcnt(0)
	v_mfma_f32_16x16x128_f8f6f4 v[78:81], v[2:9], v[186:193], v[78:81]
	v_mfma_f32_16x16x128_f8f6f4 v[74:77], v[10:17], v[186:193], v[74:77]
	v_mfma_f32_16x16x128_f8f6f4 v[70:73], v[2:9], v[194:201], v[70:73]
	v_mfma_f32_16x16x128_f8f6f4 v[66:69], v[10:17], v[194:201], v[66:69]
	v_mfma_f32_16x16x128_f8f6f4 v[46:49], v[2:9], v[202:209], v[46:49]
	v_mfma_f32_16x16x128_f8f6f4 v[42:45], v[10:17], v[202:209], v[42:45]
	v_mfma_f32_16x16x128_f8f6f4 v[38:41], v[2:9], v[210:217], v[38:41]
	v_mfma_f32_16x16x128_f8f6f4 v[34:37], v[10:17], v[210:217], v[34:37]
	s_setprio 0
	s_setprio 1
	v_mfma_f32_16x16x128_f8f6f4 v[62:65], v[220:227], v[186:193], v[62:65]
	v_mfma_f32_16x16x128_f8f6f4 v[58:61], v[228:235], v[186:193], v[58:61]
	v_mfma_f32_16x16x128_f8f6f4 v[54:57], v[220:227], v[194:201], v[54:57]
	v_mfma_f32_16x16x128_f8f6f4 v[50:53], v[228:235], v[194:201], v[50:53]
	v_mfma_f32_16x16x128_f8f6f4 v[30:33], v[220:227], v[202:209], v[30:33]
	v_mfma_f32_16x16x128_f8f6f4 v[26:29], v[228:235], v[202:209], v[26:29]
	v_mfma_f32_16x16x128_f8f6f4 v[22:25], v[220:227], v[210:217], v[22:25]
	v_mfma_f32_16x16x128_f8f6f4 v[18:21], v[228:235], v[210:217], v[18:21]
	s_setprio 0
	s_barrier
	ds_read_b128 v[2:5], v169
	ds_read_b128 v[6:9], v177
	ds_read_b128 v[10:13], v178
	ds_read_b128 v[14:17], v179
	s_add_u32 s38, s44, 0x58000
	s_addc_u32 s39, s45, 0
	s_mov_b32 m0, s64
	v_lshl_add_u64 v[220:221], s[38:39], 0, v[146:147]
	ds_read_b128 v[186:189], v184 offset:32768
	ds_read_b128 v[190:193], v184 offset:33792
	ds_read_b128 v[194:197], v184 offset:34816
	ds_read_b128 v[198:201], v184 offset:35840
	ds_read_b128 v[202:205], v184 offset:36864
	ds_read_b128 v[206:209], v184 offset:37888
	ds_read_b128 v[210:213], v184 offset:38912
	ds_read_b128 v[214:217], v184 offset:39936
	global_load_lds_dwordx4 v[220:221], off
	v_lshl_add_u64 v[220:221], s[38:39], 0, v[148:149]
	s_mov_b32 m0, s65
	s_nop 0
	global_load_lds_dwordx4 v[220:221], off
	ds_read_b128 v[220:223], v170
	ds_read_b128 v[224:227], v180
	ds_read_b128 v[228:231], v181
	ds_read_b128 v[232:235], v182
	s_waitcnt lgkmcnt(0)
	s_barrier
	s_waitcnt lgkmcnt(0)
	s_setprio 1
	s_waitcnt lgkmcnt(0)
	v_mfma_f32_16x16x128_f8f6f4 v[142:145], v[2:9], v[186:193], v[142:145]
	v_mfma_f32_16x16x128_f8f6f4 v[138:141], v[10:17], v[186:193], v[138:141]
	v_mfma_f32_16x16x128_f8f6f4 v[134:137], v[2:9], v[194:201], v[134:137]
	v_mfma_f32_16x16x128_f8f6f4 v[130:133], v[10:17], v[194:201], v[130:133]
	v_mfma_f32_16x16x128_f8f6f4 v[110:113], v[2:9], v[202:209], v[110:113]
	v_mfma_f32_16x16x128_f8f6f4 v[106:109], v[10:17], v[202:209], v[106:109]
	v_mfma_f32_16x16x128_f8f6f4 v[102:105], v[2:9], v[210:217], v[102:105]
	v_mfma_f32_16x16x128_f8f6f4 v[98:101], v[10:17], v[210:217], v[98:101]
	s_setprio 0
	s_waitcnt lgkmcnt(0)
	s_setprio 1
	s_waitcnt lgkmcnt(0)
	v_mfma_f32_16x16x128_f8f6f4 v[126:129], v[220:227], v[186:193], v[126:129]
	v_mfma_f32_16x16x128_f8f6f4 v[122:125], v[228:235], v[186:193], v[122:125]
	v_mfma_f32_16x16x128_f8f6f4 v[118:121], v[220:227], v[194:201], v[118:121]
	v_mfma_f32_16x16x128_f8f6f4 v[114:117], v[228:235], v[194:201], v[114:117]
	v_mfma_f32_16x16x128_f8f6f4 v[94:97], v[220:227], v[202:209], v[94:97]
	v_mfma_f32_16x16x128_f8f6f4 v[90:93], v[228:235], v[202:209], v[90:93]
	v_mfma_f32_16x16x128_f8f6f4 v[86:89], v[220:227], v[210:217], v[86:89]
	v_mfma_f32_16x16x128_f8f6f4 v[82:85], v[228:235], v[210:217], v[82:85]
	s_setprio 0
	s_barrier
	s_mov_b32 m0, s69
	v_lshl_add_u64 v[158:159], v[158:159], 0, s[28:29]
	global_load_lds_dwordx4 v[158:159], off
	v_lshl_add_u64 v[158:159], v[160:161], 0, s[28:29]
	s_mov_b32 m0, s70
	s_nop 0
	global_load_lds_dwordx4 v[158:159], off
	s_mov_b32 m0, s71
	v_lshl_add_u64 v[158:159], v[162:163], 0, s[28:29]
	ds_read_b128 v[186:189], v184 offset:49152
	ds_read_b128 v[190:193], v184 offset:50176
	ds_read_b128 v[194:197], v184 offset:51200
	ds_read_b128 v[198:201], v184 offset:52224
	ds_read_b128 v[202:205], v184 offset:53248
	ds_read_b128 v[206:209], v184 offset:54272
	ds_read_b128 v[210:213], v184 offset:55296
	ds_read_b128 v[214:217], v184 offset:56320
	global_load_lds_dwordx4 v[158:159], off
	v_lshl_add_u64 v[158:159], v[164:165], 0, s[28:29]
	s_mov_b32 m0, s72
	s_nop 0
	global_load_lds_dwordx4 v[158:159], off
	s_add_u32 s38, s42, 0x58080
	s_addc_u32 s39, s43, 0
	s_mov_b32 m0, s73
	v_lshl_add_u64 v[254:255], s[38:39], 0, v[146:147]
	global_load_lds_dwordx4 v[254:255], off
	v_lshl_add_u64 v[254:255], s[38:39], 0, v[148:149]
	s_mov_b32 m0, s74
	s_nop 0
	global_load_lds_dwordx4 v[254:255], off
	s_waitcnt vmcnt(6)
	s_waitcnt lgkmcnt(0)
	s_barrier
	s_waitcnt lgkmcnt(0)
	s_setprio 1
	s_waitcnt lgkmcnt(0)
	v_mfma_f32_16x16x128_f8f6f4 v[78:81], v[2:9], v[186:193], v[78:81]
	v_mfma_f32_16x16x128_f8f6f4 v[74:77], v[10:17], v[186:193], v[74:77]
	v_mfma_f32_16x16x128_f8f6f4 v[70:73], v[2:9], v[194:201], v[70:73]
	v_mfma_f32_16x16x128_f8f6f4 v[66:69], v[10:17], v[194:201], v[66:69]
	v_mfma_f32_16x16x128_f8f6f4 v[46:49], v[2:9], v[202:209], v[46:49]
	v_mfma_f32_16x16x128_f8f6f4 v[42:45], v[10:17], v[202:209], v[42:45]
	v_mfma_f32_16x16x128_f8f6f4 v[38:41], v[2:9], v[210:217], v[38:41]
	v_mfma_f32_16x16x128_f8f6f4 v[34:37], v[10:17], v[210:217], v[34:37]
	s_setprio 0
	s_setprio 1
	v_mfma_f32_16x16x128_f8f6f4 v[62:65], v[220:227], v[186:193], v[62:65]
	v_mfma_f32_16x16x128_f8f6f4 v[58:61], v[228:235], v[186:193], v[58:61]
	v_mfma_f32_16x16x128_f8f6f4 v[54:57], v[220:227], v[194:201], v[54:57]
	v_mfma_f32_16x16x128_f8f6f4 v[50:53], v[228:235], v[194:201], v[50:53]
	v_mfma_f32_16x16x128_f8f6f4 v[30:33], v[220:227], v[202:209], v[30:33]
	v_mfma_f32_16x16x128_f8f6f4 v[26:29], v[228:235], v[202:209], v[26:29]
	v_mfma_f32_16x16x128_f8f6f4 v[22:25], v[220:227], v[210:217], v[22:25]
	v_mfma_f32_16x16x128_f8f6f4 v[18:21], v[228:235], v[210:217], v[18:21]
	s_setprio 0
	s_add_i32 s86, s86, 2
	s_add_u32 s84, s84, 0x100
	s_addc_u32 s85, s85, 0
	s_cmp_gt_u32 s86, 19
	s_mov_b64 s[38:39], s[40:41]
	s_barrier
	s_cbranch_scc0 .LBB0_3123
	v_bfe_u32 v160, v0, 4, 1
	v_mul_u32_u24_e32 v160, 24, v160
	v_mov_b32_e32 v161, 0
	v_lshl_add_u32 v6, s83, 8, v166
	v_ashrrev_i32_e32 v7, 31, v6
	v_or_b32_e32 v4, 16, v6
	s_nop 15
	s_nop 15
	v_lshl_add_u64 v[2:3], v[6:7], 2, s[20:21]
	v_ashrrev_i32_e32 v5, 31, v4
	global_load_dword v158, v[2:3], off
	v_lshl_add_u64 v[8:9], v[4:5], 2, s[20:21]
	global_load_dword v159, v[8:9], off
	s_ashr_i32 s0, s82, 31
	s_lshr_b32 s0, s0, 30
	s_add_i32 s0, s82, s0
	s_and_b32 s0, s0, 0xfffffc
	v_lshlrev_b64 v[4:5], 11, v[4:5]
	s_sub_i32 s0, s82, s0
	v_lshl_add_u64 v[14:15], s[18:19], 0, v[4:5]
	v_lshl_or_b32 v4, s0, 8, v183
	v_lshlrev_b64 v[10:11], 11, v[6:7]
	v_ashrrev_i32_e32 v5, 31, v4
	v_lshl_add_u64 v[10:11], s[18:19], 0, v[10:11]
	v_lshlrev_b64 v[16:17], 1, v[4:5]
	v_lshl_add_u64 v[4:5], v[10:11], 0, v[16:17]
	v_lshl_add_u64 v[10:11], v[14:15], 0, v[16:17]
	v_or_b32_e32 v8, 32, v6
	v_ashrrev_i32_e32 v9, 31, v8
	v_lshl_add_u64 v[12:13], v[8:9], 2, s[20:21]
	v_or_b32_e32 v6, 48, v6
	v_ashrrev_i32_e32 v7, 31, v6
	v_lshlrev_b64 v[8:9], 11, v[8:9]
	v_lshlrev_b64 v[6:7], 11, v[6:7]
	v_lshl_add_u64 v[8:9], s[18:19], 0, v[8:9]
	v_lshl_add_u64 v[6:7], s[18:19], 0, v[6:7]
	v_lshl_add_u64 v[8:9], v[8:9], 0, v[16:17]
	v_lshl_add_u64 v[6:7], v[6:7], 0, v[16:17]
	s_mov_b32 s83, s80
	s_mov_b64 s[40:41], s[16:17]
	s_mov_b64 s[38:39], s[14:15]
	s_mov_b32 s82, s81
	s_waitcnt vmcnt(0)
	v_mul_f32_e32 v14, 0x3b800000, v158
	v_pk_mul_f32 v[142:143], v[142:143], v[14:15] op_sel_hi:[1,0]
	v_pk_mul_f32 v[144:145], v[144:145], v[14:15] op_sel_hi:[1,0]
	v_pk_mul_f32 v[138:139], v[138:139], v[14:15] op_sel_hi:[1,0]
	v_pk_mul_f32 v[140:141], v[140:141], v[14:15] op_sel_hi:[1,0]
	v_pk_mul_f32 v[126:127], v[126:127], v[14:15] op_sel_hi:[1,0]
	v_pk_mul_f32 v[128:129], v[128:129], v[14:15] op_sel_hi:[1,0]
	v_pk_mul_f32 v[122:123], v[122:123], v[14:15] op_sel_hi:[1,0]
	v_pk_mul_f32 v[14:15], v[124:125], v[14:15] op_sel_hi:[1,0]
	v_mul_f32_e32 v124, 0x3b800000, v159
	v_cvt_pk_bf16_f32 v126, v126, v127
	v_cvt_pk_bf16_f32 v127, v128, v129
	v_cvt_pk_bf16_f32 v122, v122, v123
	v_cvt_pk_bf16_f32 v123, v14, v15
	v_pk_mul_f32 v[14:15], v[134:135], v[124:125] op_sel_hi:[1,0]
	v_pk_mul_f32 v[128:129], v[136:137], v[124:125] op_sel_hi:[1,0]
	v_cvt_pk_bf16_f32 v142, v142, v143
	v_cvt_pk_bf16_f32 v143, v144, v145
	v_pk_mul_f32 v[130:131], v[130:131], v[124:125] op_sel_hi:[1,0]
	v_pk_mul_f32 v[132:133], v[132:133], v[124:125] op_sel_hi:[1,0]
	v_pk_mul_f32 v[118:119], v[118:119], v[124:125] op_sel_hi:[1,0]
	v_pk_mul_f32 v[120:121], v[120:121], v[124:125] op_sel_hi:[1,0]
	v_pk_mul_f32 v[114:115], v[114:115], v[124:125] op_sel_hi:[1,0]
	v_pk_mul_f32 v[116:117], v[116:117], v[124:125] op_sel_hi:[1,0]
	v_cvt_pk_bf16_f32 v14, v14, v15
	v_cvt_pk_bf16_f32 v15, v128, v129
	v_cvt_pk_bf16_f32 v138, v138, v139
	v_cvt_pk_bf16_f32 v139, v140, v141
	v_mov_b32_e32 v192, v142
	v_mov_b32_e32 v193, v143
	v_mov_b32_e32 v194, v138
	v_mov_b32_e32 v195, v139
	v_lshl_add_u64 v[162:163], v[4:5], 0, v[160:161]
	s_nop 0
	v_permlane16_swap_b32 v192, v194
	v_permlane16_swap_b32 v193, v195
	global_store_dwordx4 v[162:163], v[192:195], off
	v_mov_b32_e32 v196, v126
	v_mov_b32_e32 v197, v127
	v_mov_b32_e32 v198, v122
	v_mov_b32_e32 v199, v123
	v_lshl_add_u64 v[162:163], v[4:5], 0, v[160:161]
	s_nop 0
	v_permlane16_swap_b32 v196, v198
	v_permlane16_swap_b32 v197, v199
	global_store_dwordx4 v[162:163], v[196:199], off offset:256
	v_cvt_pk_bf16_f32 v122, v130, v131
	v_cvt_pk_bf16_f32 v123, v132, v133
	v_cvt_pk_bf16_f32 v118, v118, v119
	v_cvt_pk_bf16_f32 v119, v120, v121
	v_cvt_pk_bf16_f32 v114, v114, v115
	v_cvt_pk_bf16_f32 v115, v116, v117
	v_mov_b32_e32 v200, v14
	v_mov_b32_e32 v201, v15
	v_mov_b32_e32 v202, v122
	v_mov_b32_e32 v203, v123
	v_lshl_add_u64 v[162:163], v[10:11], 0, v[160:161]
	s_nop 0
	v_permlane16_swap_b32 v200, v202
	v_permlane16_swap_b32 v201, v203
	global_store_dwordx4 v[162:163], v[200:203], off
	v_mov_b32_e32 v204, v118
	v_mov_b32_e32 v205, v119
	v_mov_b32_e32 v206, v114
	v_mov_b32_e32 v207, v115
	v_lshl_add_u64 v[162:163], v[10:11], 0, v[160:161]
	s_nop 0
	v_permlane16_swap_b32 v204, v206
	v_permlane16_swap_b32 v205, v207
	global_store_dwordx4 v[162:163], v[204:207], off offset:256
	global_load_dword v10, v[12:13], off
	s_nop 0
	global_load_dword v11, v[2:3], off offset:192
	s_waitcnt vmcnt(0)
	v_mul_f32_e32 v10, 0x3b800000, v10
	v_mul_f32_e32 v12, 0x3b800000, v11
	v_pk_mul_f32 v[14:15], v[110:111], v[10:11] op_sel_hi:[1,0]
	v_pk_mul_f32 v[16:17], v[112:113], v[10:11] op_sel_hi:[1,0]
	v_pk_mul_f32 v[106:107], v[106:107], v[10:11] op_sel_hi:[1,0]
	v_pk_mul_f32 v[108:109], v[108:109], v[10:11] op_sel_hi:[1,0]
	v_pk_mul_f32 v[94:95], v[94:95], v[10:11] op_sel_hi:[1,0]
	v_pk_mul_f32 v[96:97], v[96:97], v[10:11] op_sel_hi:[1,0]
	v_pk_mul_f32 v[90:91], v[90:91], v[10:11] op_sel_hi:[1,0]
	v_pk_mul_f32 v[10:11], v[92:93], v[10:11] op_sel_hi:[1,0]
	v_pk_mul_f32 v[92:93], v[102:103], v[12:13] op_sel_hi:[1,0]
	v_pk_mul_f32 v[102:103], v[104:105], v[12:13] op_sel_hi:[1,0]
	v_pk_mul_f32 v[98:99], v[98:99], v[12:13] op_sel_hi:[1,0]
	v_pk_mul_f32 v[100:101], v[100:101], v[12:13] op_sel_hi:[1,0]
	v_pk_mul_f32 v[86:87], v[86:87], v[12:13] op_sel_hi:[1,0]
	v_pk_mul_f32 v[88:89], v[88:89], v[12:13] op_sel_hi:[1,0]
	v_pk_mul_f32 v[82:83], v[82:83], v[12:13] op_sel_hi:[1,0]
	v_pk_mul_f32 v[12:13], v[84:85], v[12:13] op_sel_hi:[1,0]
	v_cvt_pk_bf16_f32 v14, v14, v15
	v_cvt_pk_bf16_f32 v15, v16, v17
	v_cvt_pk_bf16_f32 v16, v106, v107
	v_cvt_pk_bf16_f32 v17, v108, v109
	v_cvt_pk_bf16_f32 v84, v94, v95
	v_cvt_pk_bf16_f32 v85, v96, v97
	v_cvt_pk_bf16_f32 v90, v90, v91
	v_cvt_pk_bf16_f32 v91, v10, v11
	v_cvt_pk_bf16_f32 v10, v92, v93
	v_cvt_pk_bf16_f32 v11, v102, v103
	v_cvt_pk_bf16_f32 v92, v98, v99
	v_cvt_pk_bf16_f32 v93, v100, v101
	v_cvt_pk_bf16_f32 v86, v86, v87
	v_cvt_pk_bf16_f32 v87, v88, v89
	v_cvt_pk_bf16_f32 v82, v82, v83
	v_cvt_pk_bf16_f32 v83, v12, v13
	v_mov_b32_e32 v208, v14
	v_mov_b32_e32 v209, v15
	v_mov_b32_e32 v210, v16
	v_mov_b32_e32 v211, v17
	v_lshl_add_u64 v[162:163], v[8:9], 0, v[160:161]
	s_nop 0
	v_permlane16_swap_b32 v208, v210
	v_permlane16_swap_b32 v209, v211
	global_store_dwordx4 v[162:163], v[208:211], off
	v_mov_b32_e32 v212, v84
	v_mov_b32_e32 v213, v85
	v_mov_b32_e32 v214, v90
	v_mov_b32_e32 v215, v91
	v_lshl_add_u64 v[162:163], v[8:9], 0, v[160:161]
	s_nop 0
	v_permlane16_swap_b32 v212, v214
	v_permlane16_swap_b32 v213, v215
	global_store_dwordx4 v[162:163], v[212:215], off offset:256
	v_mov_b32_e32 v220, v10
	v_mov_b32_e32 v221, v11
	v_mov_b32_e32 v222, v92
	v_mov_b32_e32 v223, v93
	v_lshl_add_u64 v[162:163], v[6:7], 0, v[160:161]
	s_nop 0
	v_permlane16_swap_b32 v220, v222
	v_permlane16_swap_b32 v221, v223
	global_store_dwordx4 v[162:163], v[220:223], off
	v_mov_b32_e32 v224, v86
	v_mov_b32_e32 v225, v87
	v_mov_b32_e32 v226, v82
	v_mov_b32_e32 v227, v83
	v_lshl_add_u64 v[162:163], v[6:7], 0, v[160:161]
	s_nop 0
	v_permlane16_swap_b32 v224, v226
	v_permlane16_swap_b32 v225, v227
	global_store_dwordx4 v[162:163], v[224:227], off offset:256
	global_load_dword v14, v[2:3], off offset:512
	global_load_dword v15, v[2:3], off offset:576
	v_add_co_u32_e32 v8, vcc, s76, v4
	v_lshl_add_u64 v[6:7], v[4:5], 0, s[30:31]
	s_nop 0
	v_addc_co_u32_e32 v9, vcc, 0, v5, vcc
	v_add_co_u32_e32 v12, vcc, s77, v4
	v_lshl_add_u64 v[10:11], v[4:5], 0, s[34:35]
	s_nop 0
	v_addc_co_u32_e32 v13, vcc, 0, v5, vcc
	s_and_b64 vcc, exec, s[12:13]
	s_waitcnt vmcnt(0)
	v_mul_f32_e32 v14, 0x3b800000, v14
	v_mul_f32_e32 v16, 0x3b800000, v15
	v_pk_mul_f32 v[78:79], v[78:79], v[14:15] op_sel_hi:[1,0]
	v_pk_mul_f32 v[80:81], v[80:81], v[14:15] op_sel_hi:[1,0]
	v_pk_mul_f32 v[74:75], v[74:75], v[14:15] op_sel_hi:[1,0]
	v_pk_mul_f32 v[76:77], v[76:77], v[14:15] op_sel_hi:[1,0]
	v_pk_mul_f32 v[62:63], v[62:63], v[14:15] op_sel_hi:[1,0]
	v_pk_mul_f32 v[64:65], v[64:65], v[14:15] op_sel_hi:[1,0]
	v_pk_mul_f32 v[58:59], v[58:59], v[14:15] op_sel_hi:[1,0]
	v_pk_mul_f32 v[14:15], v[60:61], v[14:15] op_sel_hi:[1,0]
	v_pk_mul_f32 v[60:61], v[70:71], v[16:17] op_sel_hi:[1,0]
	v_pk_mul_f32 v[70:71], v[72:73], v[16:17] op_sel_hi:[1,0]
	v_pk_mul_f32 v[66:67], v[66:67], v[16:17] op_sel_hi:[1,0]
	v_pk_mul_f32 v[68:69], v[68:69], v[16:17] op_sel_hi:[1,0]
	v_pk_mul_f32 v[54:55], v[54:55], v[16:17] op_sel_hi:[1,0]
	v_pk_mul_f32 v[56:57], v[56:57], v[16:17] op_sel_hi:[1,0]
	v_pk_mul_f32 v[50:51], v[50:51], v[16:17] op_sel_hi:[1,0]
	v_pk_mul_f32 v[16:17], v[52:53], v[16:17] op_sel_hi:[1,0]
	v_cvt_pk_bf16_f32 v52, v78, v79
	v_cvt_pk_bf16_f32 v53, v80, v81
	v_cvt_pk_bf16_f32 v72, v74, v75
	v_cvt_pk_bf16_f32 v73, v76, v77
	v_cvt_pk_bf16_f32 v62, v62, v63
	v_cvt_pk_bf16_f32 v63, v64, v65
	v_cvt_pk_bf16_f32 v58, v58, v59
	v_cvt_pk_bf16_f32 v59, v14, v15
	v_cvt_pk_bf16_f32 v14, v60, v61
	v_cvt_pk_bf16_f32 v15, v70, v71
	v_cvt_pk_bf16_f32 v60, v66, v67
	v_cvt_pk_bf16_f32 v61, v68, v69
	v_cvt_pk_bf16_f32 v54, v54, v55
	v_cvt_pk_bf16_f32 v55, v56, v57
	v_cvt_pk_bf16_f32 v50, v50, v51
	v_cvt_pk_bf16_f32 v51, v16, v17
	global_store_dwordx2 v[8:9], v[52:53], off
	global_store_dwordx2 v[6:7], v[72:73], off offset:32
	v_mov_b32_e32 v232, v62
	v_mov_b32_e32 v233, v63
	v_mov_b32_e32 v234, v58
	v_mov_b32_e32 v235, v59
	v_lshl_add_u64 v[162:163], v[6:7], 0, v[160:161]
	s_nop 0
	v_permlane16_swap_b32 v232, v234
	v_permlane16_swap_b32 v233, v235
	global_store_dwordx4 v[162:163], v[232:235], off offset:256
	global_store_dwordx2 v[12:13], v[14:15], off
	global_store_dwordx2 v[10:11], v[60:61], off offset:32
	v_mov_b32_e32 v236, v54
	v_mov_b32_e32 v237, v55
	v_mov_b32_e32 v238, v50
	v_mov_b32_e32 v239, v51
	v_lshl_add_u64 v[162:163], v[10:11], 0, v[160:161]
	s_nop 0
	v_permlane16_swap_b32 v236, v238
	v_permlane16_swap_b32 v237, v239
	global_store_dwordx4 v[162:163], v[236:239], off offset:256
	global_load_dword v10, v[2:3], off offset:640
	s_nop 0
	global_load_dword v11, v[2:3], off offset:704
	v_add_co_u32_e64 v6, s[12:13], s78, v4
	v_lshl_add_u64 v[2:3], v[4:5], 0, s[36:37]
	s_nop 0
	v_addc_co_u32_e64 v7, s[12:13], 0, v5, s[12:13]
	v_lshl_add_u64 v[8:9], v[4:5], 0, s[26:27]
	v_add_co_u32_e64 v4, s[12:13], s79, v4
	s_waitcnt vmcnt(0)
	v_mul_f32_e32 v10, 0x3b800000, v10
	v_mul_f32_e32 v12, 0x3b800000, v11
	v_pk_mul_f32 v[14:15], v[46:47], v[10:11] op_sel_hi:[1,0]
	v_pk_mul_f32 v[16:17], v[48:49], v[10:11] op_sel_hi:[1,0]
	v_pk_mul_f32 v[42:43], v[42:43], v[10:11] op_sel_hi:[1,0]
	v_pk_mul_f32 v[44:45], v[44:45], v[10:11] op_sel_hi:[1,0]
	v_pk_mul_f32 v[30:31], v[30:31], v[10:11] op_sel_hi:[1,0]
	v_pk_mul_f32 v[32:33], v[32:33], v[10:11] op_sel_hi:[1,0]
	v_pk_mul_f32 v[26:27], v[26:27], v[10:11] op_sel_hi:[1,0]
	v_pk_mul_f32 v[10:11], v[28:29], v[10:11] op_sel_hi:[1,0]
	v_pk_mul_f32 v[28:29], v[38:39], v[12:13] op_sel_hi:[1,0]
	v_pk_mul_f32 v[38:39], v[40:41], v[12:13] op_sel_hi:[1,0]
	v_pk_mul_f32 v[34:35], v[34:35], v[12:13] op_sel_hi:[1,0]
	v_pk_mul_f32 v[36:37], v[36:37], v[12:13] op_sel_hi:[1,0]
	v_pk_mul_f32 v[22:23], v[22:23], v[12:13] op_sel_hi:[1,0]
	v_pk_mul_f32 v[24:25], v[24:25], v[12:13] op_sel_hi:[1,0]
	v_pk_mul_f32 v[18:19], v[18:19], v[12:13] op_sel_hi:[1,0]
	v_pk_mul_f32 v[12:13], v[20:21], v[12:13] op_sel_hi:[1,0]
	v_cvt_pk_bf16_f32 v14, v14, v15
	v_cvt_pk_bf16_f32 v15, v16, v17
	v_addc_co_u32_e64 v5, s[12:13], 0, v5, s[12:13]
	v_cvt_pk_bf16_f32 v16, v42, v43
	v_cvt_pk_bf16_f32 v17, v44, v45
	v_cvt_pk_bf16_f32 v20, v30, v31
	v_cvt_pk_bf16_f32 v21, v32, v33
	v_cvt_pk_bf16_f32 v26, v26, v27
	v_cvt_pk_bf16_f32 v27, v10, v11
	v_cvt_pk_bf16_f32 v10, v28, v29
	v_cvt_pk_bf16_f32 v11, v38, v39
	v_cvt_pk_bf16_f32 v28, v34, v35
	v_cvt_pk_bf16_f32 v29, v36, v37
	v_cvt_pk_bf16_f32 v22, v22, v23
	v_cvt_pk_bf16_f32 v23, v24, v25
	v_cvt_pk_bf16_f32 v18, v18, v19
	v_cvt_pk_bf16_f32 v19, v12, v13
	global_store_dwordx2 v[6:7], v[14:15], off
	global_store_dwordx2 v[2:3], v[16:17], off offset:32
	v_mov_b32_e32 v240, v20
	v_mov_b32_e32 v241, v21
	v_mov_b32_e32 v242, v26
	v_mov_b32_e32 v243, v27
	v_lshl_add_u64 v[162:163], v[2:3], 0, v[160:161]
	s_nop 0
	v_permlane16_swap_b32 v240, v242
	v_permlane16_swap_b32 v241, v243
	global_store_dwordx4 v[162:163], v[240:243], off offset:256
	global_store_dwordx2 v[4:5], v[10:11], off
	global_store_dwordx2 v[8:9], v[28:29], off offset:32
	v_mov_b32_e32 v192, v22
	v_mov_b32_e32 v193, v23
	v_mov_b32_e32 v194, v18
	v_mov_b32_e32 v195, v19
	v_lshl_add_u64 v[162:163], v[8:9], 0, v[160:161]
	s_nop 0
	v_permlane16_swap_b32 v192, v194
	v_permlane16_swap_b32 v193, v195
	global_store_dwordx4 v[162:163], v[192:195], off offset:256
	s_cbranch_vccz .LBB0_3112
	s_waitcnt vmcnt(0)
	s_cmpk_gt_u32 s3, 0xff
	s_cbranch_scc1 .LBB0_3127
	s_barrier

.LBB0_5612:
	s_add_u32 s12, s3, 0x281ae100
	s_addc_u32 s13, s30, 0
	s_and_b32 s0, s14, 3
	s_lshl_b32 s1, s18, 13
	s_lshl_b32 s2, s0, 12
	s_add_i32 s47, s38, 0x18000
	s_mov_b64 s[14:15], 0x80
	s_add_i32 s48, s38, 0x1a000
	v_lshl_add_u64 v[6:7], v[6:7], 0, s[14:15]
	s_mov_b32 m0, s47
	s_add_u32 s16, s3, 0x1b3c3180
	s_waitcnt vmcnt(0)
	s_barrier
	global_load_lds_dwordx4 v[6:7], off
	v_lshl_add_u64 v[4:5], v[4:5], 0, s[14:15]
	s_mov_b32 m0, s48
	s_addc_u32 s17, s30, 0
	s_add_i32 s49, s38, 0x8000
	s_add_i32 s50, s38, 0xa000
	global_load_lds_dwordx4 v[4:5], off
	v_lshl_add_u64 v[4:5], s[16:17], 0, v[150:151]
	s_mov_b32 m0, s49
	s_add_u32 s20, s24, 0x20080
	global_load_lds_dwordx4 v[4:5], off
	v_lshl_add_u64 v[4:5], s[16:17], 0, v[158:159]
	s_mov_b32 m0, s50
	s_addc_u32 s21, s25, 0
	s_add_i32 s51, s38, 0x1c000
	global_load_lds_dwordx4 v[4:5], off
	v_lshl_add_u64 v[4:5], s[20:21], 0, v[148:149]
	s_mov_b32 m0, s51
	s_add_i32 s52, s38, 0x1e000
	global_load_lds_dwordx4 v[4:5], off
	v_lshl_add_u64 v[4:5], s[20:21], 0, v[146:147]
	s_mov_b32 m0, s52
	v_lshlrev_b32_e32 v7, 2, v8
	global_load_lds_dwordx4 v[4:5], off
	v_and_b32_e32 v4, 3, v9
	v_lshlrev_b32_e32 v5, 4, v4
	v_lshlrev_b32_e32 v6, 6, v8
	v_and_b32_e32 v7, 32, v7
	v_bitop3_b32 v5, v6, v7, v5 bitop3:0x36
	s_waitcnt vmcnt(6)
	s_add_i32 s2, s2, 0
	v_lshl_add_u64 v[152:153], v[2:3], 2, s[8:9]
	v_add_u32_e32 v2, s2, v5
	v_add_u32_e32 v3, 0, v5
	v_lshlrev_b32_e32 v4, 2, v4
	v_lshl_or_b32 v159, s18, 6, v8
	v_add_u32_e32 v179, 0x10000, v2
	v_add_u32_e32 v180, 0x14000, v2
	v_add_u32_e32 v181, 0x18000, v2
	v_add_u32_e32 v182, 0x1c000, v2
	v_lshl_or_b32 v183, s0, 4, v4
	v_add_u32_e32 v184, 0x10400, v2
	v_add_u32_e32 v185, 0x10800, v2
	v_add_u32_e32 v186, 0x10c00, v2
	v_add_u32_e32 v187, 0x14400, v2
	v_add_u32_e32 v188, 0x14800, v2
	v_add_u32_e32 v189, 0x14c00, v2
	v_add_u32_e32 v190, 0x18400, v2
	v_add_u32_e32 v191, 0x18800, v2
	v_add_u32_e32 v192, 0x18c00, v2
	v_add_u32_e32 v193, 0x1c400, v2
	v_add_u32_e32 v194, 0x1c800, v2
	v_add_u32_e32 v195, 0x1cc00, v2
	s_ashr_i32 s53, s33, 31
	v_mov_b64_e32 v[154:155], 0x1600
	v_mov_b64_e32 v[156:157], 0x15ff
	v_add_u32_e32 v196, s1, v3
	s_mov_b32 s55, 0xc3dc0000
	s_movk_i32 s58, 0xb00
	v_mov_b32_e32 v197, 0x43dc0000
	v_mov_b32_e32 v200, v150
	s_barrier

.LBB0_5616:
	ds_read2_b32 v[2:3], v178 offset1:16
	s_add_u32 s0, s3, s24
	s_addc_u32 s1, s30, s25
	s_add_u32 s0, s0, 0x1b3c3200
	ds_read2_b32 v[168:169], v178 offset0:32 offset1:48
	s_waitcnt lgkmcnt(0)
	v_lshl_add_u32 v161, v2, 10, v1
	v_lshl_add_u32 v163, v3, 10, v176
	ds_read_b128 v[2:5], v179
	ds_read_b128 v[6:9], v184
	ds_read_b128 v[10:13], v185
	ds_read_b128 v[14:17], v186
	s_addc_u32 s1, s1, 0
	s_add_u32 s2, s62, s24
	s_addc_u32 s4, s63, s25
	s_cmpk_eq_i32 s24, 0x300
	s_cselect_b64 vcc, -1, 0
	s_and_b64 s[26:27], vcc, exec
	v_lshl_add_u32 v198, v168, 10, v1
	v_lshl_add_u32 v199, v169, 10, v176
	v_cndmask_b32_e32 v150, v200, v161, vcc
	s_cselect_b32 s29, s11, s1
	s_cselect_b32 s28, s10, s0
	v_cndmask_b32_e32 v172, v158, v163, vcc
	v_cndmask_b32_e32 v201, v160, v198, vcc
	s_cselect_b32 s27, s19, s4
	s_cselect_b32 s26, s61, s2
	v_cndmask_b32_e32 v219, v162, v199, vcc
	v_lshl_add_u64 v[168:169], v[166:167], 0, s[24:25]
	s_add_i32 m0, s38, 0xc000
	ds_read_b128 v[202:205], v196
	ds_read_b128 v[206:209], v196 offset:1024
	ds_read_b128 v[210:213], v196 offset:2048
	ds_read_b128 v[214:217], v196 offset:3072
	ds_read_b128 v[220:223], v196 offset:4096
	ds_read_b128 v[224:227], v196 offset:5120
	ds_read_b128 v[228:231], v196 offset:6144
	ds_read_b128 v[232:235], v196 offset:7168
	global_load_lds_dwordx4 v[168:169], off
	v_lshl_add_u64 v[168:169], v[164:165], 0, s[24:25]
	s_add_i32 m0, s38, 0xe000
	s_nop 0
	global_load_lds_dwordx4 v[168:169], off
	ds_read_b128 v[236:239], v180
	ds_read_b128 v[240:243], v187
	ds_read_b128 v[244:247], v188
	ds_read_b128 v[248:251], v189
	s_waitcnt lgkmcnt(0)
	s_barrier
	s_waitcnt lgkmcnt(0)
	s_setprio 1
	s_waitcnt lgkmcnt(0)
	v_mfma_f32_16x16x128_f8f6f4 v[142:145], v[2:9], v[202:209], v[142:145]
	v_mfma_f32_16x16x128_f8f6f4 v[138:141], v[10:17], v[202:209], v[138:141]
	v_mfma_f32_16x16x128_f8f6f4 v[126:129], v[2:9], v[210:217], v[126:129]
	v_mfma_f32_16x16x128_f8f6f4 v[122:125], v[10:17], v[210:217], v[122:125]
	v_mfma_f32_16x16x128_f8f6f4 v[110:113], v[2:9], v[220:227], v[110:113]
	v_mfma_f32_16x16x128_f8f6f4 v[106:109], v[10:17], v[220:227], v[106:109]
	v_mfma_f32_16x16x128_f8f6f4 v[94:97], v[2:9], v[228:235], v[94:97]
	v_mfma_f32_16x16x128_f8f6f4 v[90:93], v[10:17], v[228:235], v[90:93]
	s_setprio 0
	s_waitcnt lgkmcnt(0)
	s_setprio 1
	s_waitcnt lgkmcnt(0)
	v_mfma_f32_16x16x128_f8f6f4 v[134:137], v[236:243], v[202:209], v[134:137]
	v_mfma_f32_16x16x128_f8f6f4 v[130:133], v[244:251], v[202:209], v[130:133]
	v_mfma_f32_16x16x128_f8f6f4 v[118:121], v[236:243], v[210:217], v[118:121]
	v_mfma_f32_16x16x128_f8f6f4 v[114:117], v[244:251], v[210:217], v[114:117]
	v_mfma_f32_16x16x128_f8f6f4 v[102:105], v[236:243], v[220:227], v[102:105]
	v_mfma_f32_16x16x128_f8f6f4 v[98:101], v[244:251], v[220:227], v[98:101]
	v_mfma_f32_16x16x128_f8f6f4 v[86:89], v[236:243], v[228:235], v[86:89]
	v_mfma_f32_16x16x128_f8f6f4 v[82:85], v[244:251], v[228:235], v[82:85]
	s_setprio 0
	s_barrier
	s_mov_b32 m0, s39
	v_lshl_add_u64 v[168:169], s[26:27], 0, v[148:149]
	global_load_lds_dwordx4 v[168:169], off
	v_lshl_add_u64 v[170:171], s[26:27], 0, v[146:147]
	s_mov_b32 m0, s40
	s_nop 0
	global_load_lds_dwordx4 v[170:171], off
	s_mov_b32 m0, s38
	ds_read_b128 v[202:205], v196 offset:16384
	ds_read_b128 v[206:209], v196 offset:17408
	ds_read_b128 v[210:213], v196 offset:18432
	ds_read_b128 v[214:217], v196 offset:19456
	ds_read_b128 v[220:223], v196 offset:20480
	ds_read_b128 v[224:227], v196 offset:21504
	ds_read_b128 v[228:231], v196 offset:22528
	ds_read_b128 v[232:235], v196 offset:23552
	global_load_lds_dwordx4 v150, s[28:29]
	s_mov_b32 m0, s41
	v_mov_b32_e32 v173, v151
	global_load_lds_dwordx4 v172, s[28:29]
	v_lshl_add_u64 v[174:175], s[28:29], 0, v[150:151]
	v_lshl_add_u64 v[172:173], s[28:29], 0, v[172:173]
	s_add_u32 s66, s26, 0x20000
	s_addc_u32 s67, s27, 0
	s_mov_b32 m0, s42
	v_lshl_add_u64 v[254:255], s[66:67], 0, v[148:149]
	global_load_lds_dwordx4 v[254:255], off
	v_lshl_add_u64 v[254:255], s[66:67], 0, v[146:147]
	s_mov_b32 m0, s43
	s_nop 0
	global_load_lds_dwordx4 v[254:255], off
	s_waitcnt vmcnt(6)
	s_waitcnt lgkmcnt(0)
	s_barrier
	s_waitcnt lgkmcnt(0)
	s_setprio 1
	s_waitcnt lgkmcnt(0)
	v_mfma_f32_16x16x128_f8f6f4 v[78:81], v[2:9], v[202:209], v[78:81]
	v_mfma_f32_16x16x128_f8f6f4 v[74:77], v[10:17], v[202:209], v[74:77]
	v_mfma_f32_16x16x128_f8f6f4 v[62:65], v[2:9], v[210:217], v[62:65]
	v_mfma_f32_16x16x128_f8f6f4 v[58:61], v[10:17], v[210:217], v[58:61]
	v_mfma_f32_16x16x128_f8f6f4 v[46:49], v[2:9], v[220:227], v[46:49]
	v_mfma_f32_16x16x128_f8f6f4 v[42:45], v[10:17], v[220:227], v[42:45]
	v_mfma_f32_16x16x128_f8f6f4 v[30:33], v[2:9], v[228:235], v[30:33]
	v_mfma_f32_16x16x128_f8f6f4 v[26:29], v[10:17], v[228:235], v[26:29]
	s_setprio 0
	s_setprio 1
	v_mfma_f32_16x16x128_f8f6f4 v[70:73], v[236:243], v[202:209], v[70:73]
	v_mfma_f32_16x16x128_f8f6f4 v[66:69], v[244:251], v[202:209], v[66:69]
	v_mfma_f32_16x16x128_f8f6f4 v[54:57], v[236:243], v[210:217], v[54:57]
	v_mfma_f32_16x16x128_f8f6f4 v[50:53], v[244:251], v[210:217], v[50:53]
	v_mfma_f32_16x16x128_f8f6f4 v[38:41], v[236:243], v[220:227], v[38:41]
	v_mfma_f32_16x16x128_f8f6f4 v[34:37], v[244:251], v[220:227], v[34:37]
	v_mfma_f32_16x16x128_f8f6f4 v[22:25], v[236:243], v[228:235], v[22:25]
	v_mfma_f32_16x16x128_f8f6f4 v[18:21], v[244:251], v[228:235], v[18:21]
	s_setprio 0
	s_barrier
	ds_read_b128 v[2:5], v181
	ds_read_b128 v[6:9], v190
	ds_read_b128 v[10:13], v191
	ds_read_b128 v[14:17], v192
	s_mov_b32 m0, s44
	ds_read_b128 v[202:205], v196 offset:32768
	ds_read_b128 v[206:209], v196 offset:33792
	ds_read_b128 v[210:213], v196 offset:34816
	ds_read_b128 v[214:217], v196 offset:35840
	ds_read_b128 v[220:223], v196 offset:36864
	ds_read_b128 v[224:227], v196 offset:37888
	ds_read_b128 v[228:231], v196 offset:38912
	ds_read_b128 v[232:235], v196 offset:39936
	global_load_lds_dwordx4 v201, s[28:29]
	s_mov_b32 m0, s45
	s_nop 0
	global_load_lds_dwordx4 v219, s[28:29]
	ds_read_b128 v[236:239], v182
	ds_read_b128 v[240:243], v193
	ds_read_b128 v[244:247], v194
	ds_read_b128 v[248:251], v195
	s_waitcnt lgkmcnt(0)
	s_barrier
	s_waitcnt lgkmcnt(0)
	s_setprio 1
	s_waitcnt lgkmcnt(0)
	v_mfma_f32_16x16x128_f8f6f4 v[142:145], v[2:9], v[202:209], v[142:145]
	v_mfma_f32_16x16x128_f8f6f4 v[138:141], v[10:17], v[202:209], v[138:141]
	v_mfma_f32_16x16x128_f8f6f4 v[126:129], v[2:9], v[210:217], v[126:129]
	v_mfma_f32_16x16x128_f8f6f4 v[122:125], v[10:17], v[210:217], v[122:125]
	v_mfma_f32_16x16x128_f8f6f4 v[110:113], v[2:9], v[220:227], v[110:113]
	v_mfma_f32_16x16x128_f8f6f4 v[106:109], v[10:17], v[220:227], v[106:109]
	v_mfma_f32_16x16x128_f8f6f4 v[94:97], v[2:9], v[228:235], v[94:97]
	v_mfma_f32_16x16x128_f8f6f4 v[90:93], v[10:17], v[228:235], v[90:93]
	s_setprio 0
	s_waitcnt lgkmcnt(0)
	s_setprio 1
	s_waitcnt lgkmcnt(0)
	v_mfma_f32_16x16x128_f8f6f4 v[134:137], v[236:243], v[202:209], v[134:137]
	v_mfma_f32_16x16x128_f8f6f4 v[130:133], v[244:251], v[202:209], v[130:133]
	v_mfma_f32_16x16x128_f8f6f4 v[118:121], v[236:243], v[210:217], v[118:121]
	v_mfma_f32_16x16x128_f8f6f4 v[114:117], v[244:251], v[210:217], v[114:117]
	v_mfma_f32_16x16x128_f8f6f4 v[102:105], v[236:243], v[220:227], v[102:105]
	v_mfma_f32_16x16x128_f8f6f4 v[98:101], v[244:251], v[220:227], v[98:101]
	v_mfma_f32_16x16x128_f8f6f4 v[86:89], v[236:243], v[228:235], v[86:89]
	v_mfma_f32_16x16x128_f8f6f4 v[82:85], v[244:251], v[228:235], v[82:85]
	s_setprio 0
	s_barrier
	s_mov_b32 m0, s47
	v_lshl_add_u64 v[168:169], v[168:169], 0, s[14:15]
	global_load_lds_dwordx4 v[168:169], off
	v_lshl_add_u64 v[168:169], v[170:171], 0, s[14:15]
	s_mov_b32 m0, s48
	s_nop 0
	global_load_lds_dwordx4 v[168:169], off
	s_mov_b32 m0, s49
	v_lshl_add_u64 v[168:169], v[174:175], 0, s[14:15]
	ds_read_b128 v[202:205], v196 offset:49152
	ds_read_b128 v[206:209], v196 offset:50176
	ds_read_b128 v[210:213], v196 offset:51200
	ds_read_b128 v[214:217], v196 offset:52224
	ds_read_b128 v[220:223], v196 offset:53248
	ds_read_b128 v[224:227], v196 offset:54272
	ds_read_b128 v[228:231], v196 offset:55296
	ds_read_b128 v[232:235], v196 offset:56320
	global_load_lds_dwordx4 v[168:169], off
	v_lshl_add_u64 v[168:169], v[172:173], 0, s[14:15]
	s_mov_b32 m0, s50
	s_nop 0
	global_load_lds_dwordx4 v[168:169], off
	s_add_u32 s26, s26, 0x20080
	s_addc_u32 s27, s27, 0
	s_mov_b32 m0, s51
	v_lshl_add_u64 v[254:255], s[26:27], 0, v[148:149]
	global_load_lds_dwordx4 v[254:255], off
	v_lshl_add_u64 v[254:255], s[26:27], 0, v[146:147]
	s_mov_b32 m0, s52
	s_nop 0
	global_load_lds_dwordx4 v[254:255], off
	s_waitcnt vmcnt(6)
	s_waitcnt lgkmcnt(0)
	s_barrier
	s_waitcnt lgkmcnt(0)
	s_setprio 1
	s_waitcnt lgkmcnt(0)
	v_mfma_f32_16x16x128_f8f6f4 v[78:81], v[2:9], v[202:209], v[78:81]
	v_mfma_f32_16x16x128_f8f6f4 v[74:77], v[10:17], v[202:209], v[74:77]
	v_mfma_f32_16x16x128_f8f6f4 v[62:65], v[2:9], v[210:217], v[62:65]
	v_mfma_f32_16x16x128_f8f6f4 v[58:61], v[10:17], v[210:217], v[58:61]
	v_mfma_f32_16x16x128_f8f6f4 v[46:49], v[2:9], v[220:227], v[46:49]
	v_mfma_f32_16x16x128_f8f6f4 v[42:45], v[10:17], v[220:227], v[42:45]
	v_mfma_f32_16x16x128_f8f6f4 v[30:33], v[2:9], v[228:235], v[30:33]
	v_mfma_f32_16x16x128_f8f6f4 v[26:29], v[10:17], v[228:235], v[26:29]
	s_setprio 0
	s_setprio 1
	v_mfma_f32_16x16x128_f8f6f4 v[70:73], v[236:243], v[202:209], v[70:73]
	v_mfma_f32_16x16x128_f8f6f4 v[66:69], v[244:251], v[202:209], v[66:69]
	v_mfma_f32_16x16x128_f8f6f4 v[54:57], v[236:243], v[210:217], v[54:57]
	v_mfma_f32_16x16x128_f8f6f4 v[50:53], v[244:251], v[210:217], v[50:53]
	v_mfma_f32_16x16x128_f8f6f4 v[38:41], v[236:243], v[220:227], v[38:41]
	v_mfma_f32_16x16x128_f8f6f4 v[34:37], v[244:251], v[220:227], v[34:37]
	v_mfma_f32_16x16x128_f8f6f4 v[22:25], v[236:243], v[228:235], v[22:25]
	v_mfma_f32_16x16x128_f8f6f4 v[18:21], v[244:251], v[228:235], v[18:21]
	s_setprio 0
	s_add_i32 s64, s64, 2
	s_add_u32 s24, s24, 0x100
	s_addc_u32 s25, s25, 0
	s_cmp_gt_u32 s64, 5
	s_barrier
	s_cbranch_scc0 .LBB0_5616
	v_mul_f32_e32 v2, 0xbd38aa3b, v142
	v_exp_f32_e32 v4, v2
	v_mul_f32_e32 v5, 0x3d000000, v143
	v_mul_f32_e32 v7, 0xbd38aa3b, v143
	v_exp_f32_e32 v7, v7
	v_add_f32_e32 v4, 1.0, v4
	v_rcp_f32_e32 v4, v4
	v_mul_f32_e32 v10, 0x3d000000, v140
	v_mul_f32_e32 v12, 0x3d000000, v135
	v_mul_f32_e32 v3, v142, v4
	v_add_f32_e32 v4, 1.0, v7
	v_rcp_f32_e32 v4, v4
	v_mul_f32_e32 v3, v138, v3
	v_mul_f32_e32 v3, 0x3b800000, v3
	v_med3_f32 v7, v3, s55, v197
	v_mul_f32_e32 v4, v143, v4
	v_mul_f32_e32 v8, 0xbd38aa3b, v144
	v_exp_f32_e32 v8, v8
	v_mul_f32_e32 v3, v139, v4
	v_mul_f32_e32 v3, 0x3b800000, v3
	v_add_f32_e32 v4, 1.0, v8
	v_mul_f32_e32 v9, 0xbd38aa3b, v145
	v_rcp_f32_e32 v4, v4
	v_exp_f32_e32 v9, v9
	v_med3_f32 v3, v3, s55, v197
	v_cvt_pk_fp8_f32 v7, v7, v3
	v_mul_f32_e32 v4, v144, v4
	v_add_f32_e32 v5, 1.0, v9
	v_rcp_f32_e32 v5, v5
	v_mul_f32_e32 v4, v140, v4
	v_mul_f32_e32 v4, 0x3b800000, v4
	v_mul_f32_e32 v5, v145, v5
	v_mul_f32_e32 v3, v141, v5
	v_mul_f32_e32 v3, 0x3b800000, v3
	v_med3_f32 v4, v4, s55, v197
	v_med3_f32 v3, v3, s55, v197
	v_cvt_pk_fp8_f32 v7, v4, v3 op_sel:[0,0,1]
	v_mul_f32_e32 v3, 0xbd38aa3b, v134
	v_exp_f32_e32 v11, v3
	v_mul_f32_e32 v13, 0xbd38aa3b, v135
	v_exp_f32_e32 v13, v13
	v_add_f32_e32 v11, 1.0, v11
	v_rcp_f32_e32 v11, v11
	s_mul_hi_i32 s0, s22, 0x2e8ba2e9
	s_lshr_b32 s1, s0, 31
	s_lshr_b32 s0, s0, 2
	v_mul_f32_e32 v10, v134, v11
	v_add_f32_e32 v11, 1.0, v13
	v_rcp_f32_e32 v11, v11
	v_mul_f32_e32 v10, v130, v10
	v_mul_f32_e32 v10, 0x3b800000, v10
	v_mul_f32_e32 v11, v135, v11
	v_mul_f32_e32 v14, 0xbd38aa3b, v136
	v_exp_f32_e32 v14, v14
	v_mul_f32_e32 v11, v131, v11
	v_mul_f32_e32 v11, 0x3b800000, v11
	v_med3_f32 v10, v10, s55, v197
	v_add_f32_e32 v13, 1.0, v14
	v_mul_f32_e32 v14, 0x3d000000, v137
	v_mul_f32_e32 v15, 0xbd38aa3b, v137
	v_rcp_f32_e32 v13, v13
	v_exp_f32_e32 v15, v15
	v_med3_f32 v11, v11, s55, v197
	v_mul_f32_e32 v16, 0x3d000000, v132
	v_mul_f32_e32 v12, v136, v13
	v_add_f32_e32 v13, 1.0, v15
	v_rcp_f32_e32 v13, v13
	v_cvt_pk_fp8_f32 v10, v10, v11
	s_add_i32 s0, s0, s1
	v_mul_f32_e32 v13, v137, v13
	v_mul_f32_e32 v12, v132, v12
	v_mul_f32_e32 v11, v133, v13
	s_mul_i32 s0, s0, 22
	v_mul_f32_e32 v12, 0x3b800000, v12
	v_mul_f32_e32 v11, 0x3b800000, v11
	s_sub_i32 s0, s22, s0
	v_med3_f32 v12, v12, s55, v197
	v_med3_f32 v11, v11, s55, v197
	v_lshl_add_u32 v6, s60, 8, v159
	v_lshl_or_b32 v2, s0, 7, v183
	v_mov_b64_e32 v[4:5], s[12:13]
	v_cvt_pk_fp8_f32 v10, v12, v11 op_sel:[0,0,1]
	v_mad_i64_i32 v[8:9], s[24:25], v6, s58, v[4:5]
	v_ashrrev_i32_e32 v3, 31, v2
	v_lshl_add_u64 v[8:9], v[8:9], 0, v[2:3]
	s_nop 15
	s_nop 15
	global_store_dword v[8:9], v7, off
	global_store_dword v[8:9], v10, off offset:64
	v_mul_f32_e32 v12, 0xbd38aa3b, v126
	v_mul_f32_e32 v10, 0xbd38aa3b, v127
	v_exp_f32_e32 v12, v12
	v_exp_f32_e32 v10, v10
	v_mul_f32_e32 v14, 0x3d000000, v124
	v_or_b32_e32 v7, 16, v6
	v_add_f32_e32 v8, 1.0, v12
	v_add_f32_e32 v10, 1.0, v10
	v_rcp_f32_e32 v8, v8
	v_rcp_f32_e32 v10, v10
	v_mul_f32_e32 v16, 0x3d000000, v116
	v_mul_f32_e32 v8, v126, v8
	v_mul_f32_e32 v9, v127, v10
	v_mul_f32_e32 v8, v122, v8
	v_mul_f32_e32 v12, 0xbd38aa3b, v128
	v_exp_f32_e32 v12, v12
	v_mul_f32_e32 v8, 0x3b800000, v8
	v_med3_f32 v11, v8, s55, v197
	v_mul_f32_e32 v8, v123, v9
	v_add_f32_e32 v9, 1.0, v12
	v_mul_f32_e32 v13, 0xbd38aa3b, v129
	v_rcp_f32_e32 v9, v9
	v_exp_f32_e32 v13, v13
	v_mul_f32_e32 v8, 0x3b800000, v8
	v_med3_f32 v8, v8, s55, v197
	v_mul_f32_e32 v9, v128, v9
	v_add_f32_e32 v10, 1.0, v13
	v_rcp_f32_e32 v10, v10
	v_cvt_pk_fp8_f32 v11, v11, v8
	v_mul_f32_e32 v9, v124, v9
	v_mul_f32_e32 v10, v129, v10
	v_mul_f32_e32 v8, v125, v10
	v_mul_f32_e32 v9, 0x3b800000, v9
	v_mul_f32_e32 v8, 0x3b800000, v8
	v_med3_f32 v9, v9, s55, v197
	v_med3_f32 v8, v8, s55, v197
	v_cvt_pk_fp8_f32 v11, v9, v8 op_sel:[0,0,1]
	v_mul_f32_e32 v8, 0xbd38aa3b, v118
	v_exp_f32_e32 v12, v8
	v_mad_i64_i32 v[8:9], s[24:25], v7, s58, v[4:5]
	v_add_f32_e32 v7, 1.0, v12
	v_mul_f32_e32 v12, 0x3d000000, v119
	v_mul_f32_e32 v13, 0xbd38aa3b, v119
	v_rcp_f32_e32 v7, v7
	v_exp_f32_e32 v13, v13
	v_lshl_add_u64 v[8:9], v[8:9], 0, v[2:3]
	s_and_b64 vcc, exec, s[8:9]
	v_mul_f32_e32 v7, v118, v7
	v_add_f32_e32 v10, 1.0, v13
	v_rcp_f32_e32 v10, v10
	v_mul_f32_e32 v7, v114, v7
	v_mul_f32_e32 v7, 0x3b800000, v7
	v_mul_f32_e32 v10, v119, v10
	v_mul_f32_e32 v14, 0xbd38aa3b, v120
	v_exp_f32_e32 v14, v14
	v_mul_f32_e32 v10, v115, v10
	v_mul_f32_e32 v10, 0x3b800000, v10
	v_med3_f32 v7, v7, s55, v197
	v_add_f32_e32 v13, 1.0, v14
	v_mul_f32_e32 v14, 0x3d000000, v121
	v_mul_f32_e32 v15, 0xbd38aa3b, v121
	v_rcp_f32_e32 v13, v13
	v_exp_f32_e32 v15, v15
	v_med3_f32 v10, v10, s55, v197
	v_cvt_pk_fp8_f32 v7, v7, v10
	v_mul_f32_e32 v12, v120, v13
	v_add_f32_e32 v13, 1.0, v15
	v_rcp_f32_e32 v13, v13
	v_mul_f32_e32 v12, v116, v12
	v_mul_f32_e32 v12, 0x3b800000, v12
	v_mul_f32_e32 v13, v121, v13
	v_mul_f32_e32 v10, v117, v13
	v_mul_f32_e32 v10, 0x3b800000, v10
	v_med3_f32 v12, v12, s55, v197
	v_med3_f32 v10, v10, s55, v197
	v_cvt_pk_fp8_f32 v7, v12, v10 op_sel:[0,0,1]
	v_mul_f32_e32 v12, 0xbd38aa3b, v110
	v_exp_f32_e32 v12, v12
	global_store_dword v[8:9], v11, off
	global_store_dword v[8:9], v7, off offset:64
	v_mul_f32_e32 v11, 0xbd38aa3b, v111
	v_add_f32_e32 v8, 1.0, v12
	v_rcp_f32_e32 v8, v8
	v_exp_f32_e32 v11, v11
	v_mul_f32_e32 v14, 0x3d000000, v108
	v_mul_f32_e32 v8, v110, v8
	v_add_f32_e32 v10, 1.0, v11
	v_rcp_f32_e32 v10, v10
	v_mul_f32_e32 v8, v106, v8
	v_mul_f32_e32 v8, 0x3b800000, v8
	v_med3_f32 v11, v8, s55, v197
	v_mul_f32_e32 v9, v111, v10
	v_mul_f32_e32 v12, 0xbd38aa3b, v112
	v_exp_f32_e32 v12, v12
	v_mul_f32_e32 v8, v107, v9
	v_mul_f32_e32 v8, 0x3b800000, v8
	v_add_f32_e32 v9, 1.0, v12
	v_mul_f32_e32 v13, 0xbd38aa3b, v113
	v_rcp_f32_e32 v9, v9
	v_exp_f32_e32 v13, v13
	v_med3_f32 v8, v8, s55, v197
	v_cvt_pk_fp8_f32 v11, v11, v8
	v_mul_f32_e32 v9, v112, v9
	v_add_f32_e32 v10, 1.0, v13
	v_rcp_f32_e32 v10, v10
	v_mul_f32_e32 v9, v108, v9
	v_mul_f32_e32 v9, 0x3b800000, v9
	v_mul_f32_e32 v10, v113, v10
	v_mul_f32_e32 v8, v109, v10
	v_mul_f32_e32 v8, 0x3b800000, v8
	v_med3_f32 v9, v9, s55, v197
	v_med3_f32 v8, v8, s55, v197
	v_cvt_pk_fp8_f32 v11, v9, v8 op_sel:[0,0,1]
	v_mul_f32_e32 v8, 0xbd38aa3b, v102
	v_exp_f32_e32 v12, v8
	v_or_b32_e32 v7, 32, v6
	v_mad_i64_i32 v[8:9], s[24:25], v7, s58, v[4:5]
	v_add_f32_e32 v7, 1.0, v12
	v_mul_f32_e32 v12, 0x3d000000, v103
	v_mul_f32_e32 v13, 0xbd38aa3b, v103
	v_rcp_f32_e32 v7, v7
	v_exp_f32_e32 v13, v13
	v_mul_f32_e32 v16, 0x3d000000, v100
	v_mul_f32_e32 v7, v102, v7
	v_add_f32_e32 v10, 1.0, v13
	v_rcp_f32_e32 v10, v10
	v_mul_f32_e32 v7, v98, v7
	v_mul_f32_e32 v7, 0x3b800000, v7
	v_mul_f32_e32 v10, v103, v10
	v_mul_f32_e32 v14, 0xbd38aa3b, v104
	v_exp_f32_e32 v14, v14
	v_mul_f32_e32 v10, v99, v10
	v_mul_f32_e32 v10, 0x3b800000, v10
	v_med3_f32 v7, v7, s55, v197
	v_add_f32_e32 v13, 1.0, v14
	v_mul_f32_e32 v14, 0x3d000000, v105
	v_mul_f32_e32 v15, 0xbd38aa3b, v105
	v_rcp_f32_e32 v13, v13
	v_exp_f32_e32 v15, v15
	v_med3_f32 v10, v10, s55, v197
	v_cvt_pk_fp8_f32 v7, v7, v10
	v_mul_f32_e32 v12, v104, v13
	v_add_f32_e32 v13, 1.0, v15
	v_rcp_f32_e32 v13, v13
	v_mul_f32_e32 v12, v100, v12
	v_mul_f32_e32 v12, 0x3b800000, v12
	v_mul_f32_e32 v13, v105, v13
	v_mul_f32_e32 v10, v101, v13
	v_mul_f32_e32 v10, 0x3b800000, v10
	v_med3_f32 v12, v12, s55, v197
	v_med3_f32 v10, v10, s55, v197
	v_cvt_pk_fp8_f32 v7, v12, v10 op_sel:[0,0,1]
	v_mul_f32_e32 v12, 0xbd38aa3b, v94
	v_exp_f32_e32 v12, v12
	v_lshl_add_u64 v[8:9], v[8:9], 0, v[2:3]
	global_store_dword v[8:9], v11, off
	global_store_dword v[8:9], v7, off offset:64
	v_add_f32_e32 v8, 1.0, v12
	v_mul_f32_e32 v11, 0xbd38aa3b, v95
	v_rcp_f32_e32 v8, v8
	v_exp_f32_e32 v11, v11
	v_mul_f32_e32 v14, 0x3d000000, v92
	v_mul_f32_e32 v8, v94, v8
	v_add_f32_e32 v10, 1.0, v11
	v_rcp_f32_e32 v10, v10
	v_mul_f32_e32 v8, v90, v8
	v_mul_f32_e32 v8, 0x3b800000, v8
	v_med3_f32 v11, v8, s55, v197
	v_mul_f32_e32 v9, v95, v10
	v_mul_f32_e32 v12, 0xbd38aa3b, v96
	v_exp_f32_e32 v12, v12
	v_mul_f32_e32 v8, v91, v9
	v_mul_f32_e32 v8, 0x3b800000, v8
	v_add_f32_e32 v9, 1.0, v12
	v_mul_f32_e32 v13, 0xbd38aa3b, v97
	v_rcp_f32_e32 v9, v9
	v_exp_f32_e32 v13, v13
	v_med3_f32 v8, v8, s55, v197
	v_cvt_pk_fp8_f32 v11, v11, v8
	v_mul_f32_e32 v9, v96, v9
	v_add_f32_e32 v10, 1.0, v13
	v_rcp_f32_e32 v10, v10
	v_mul_f32_e32 v9, v92, v9
	v_mul_f32_e32 v9, 0x3b800000, v9
	v_mul_f32_e32 v10, v97, v10
	v_mul_f32_e32 v8, v93, v10
	v_mul_f32_e32 v8, 0x3b800000, v8
	v_med3_f32 v9, v9, s55, v197
	v_med3_f32 v8, v8, s55, v197
	v_cvt_pk_fp8_f32 v11, v9, v8 op_sel:[0,0,1]
	v_mul_f32_e32 v8, 0xbd38aa3b, v86
	v_exp_f32_e32 v12, v8
	v_or_b32_e32 v7, 48, v6
	v_mad_i64_i32 v[8:9], s[24:25], v7, s58, v[4:5]
	v_add_f32_e32 v7, 1.0, v12
	v_mul_f32_e32 v12, 0x3d000000, v87
	v_mul_f32_e32 v13, 0xbd38aa3b, v87
	v_rcp_f32_e32 v7, v7
	v_exp_f32_e32 v13, v13
	v_mul_f32_e32 v16, 0x3d000000, v84
	v_mul_f32_e32 v7, v86, v7
	v_add_f32_e32 v10, 1.0, v13
	v_rcp_f32_e32 v10, v10
	v_mul_f32_e32 v7, v82, v7
	v_mul_f32_e32 v7, 0x3b800000, v7
	v_mul_f32_e32 v10, v87, v10
	v_mul_f32_e32 v14, 0xbd38aa3b, v88
	v_exp_f32_e32 v14, v14
	v_mul_f32_e32 v10, v83, v10
	v_mul_f32_e32 v10, 0x3b800000, v10
	v_med3_f32 v7, v7, s55, v197
	v_add_f32_e32 v13, 1.0, v14
	v_mul_f32_e32 v14, 0x3d000000, v89
	v_mul_f32_e32 v15, 0xbd38aa3b, v89
	v_rcp_f32_e32 v13, v13
	v_exp_f32_e32 v15, v15
	v_med3_f32 v10, v10, s55, v197
	v_cvt_pk_fp8_f32 v7, v7, v10
	v_mul_f32_e32 v12, v88, v13
	v_add_f32_e32 v13, 1.0, v15
	v_rcp_f32_e32 v13, v13
	v_mul_f32_e32 v12, v84, v12
	v_mul_f32_e32 v12, 0x3b800000, v12
	v_mul_f32_e32 v13, v89, v13
	v_mul_f32_e32 v10, v85, v13
	v_mul_f32_e32 v10, 0x3b800000, v10
	v_med3_f32 v12, v12, s55, v197
	v_med3_f32 v10, v10, s55, v197
	v_cvt_pk_fp8_f32 v7, v12, v10 op_sel:[0,0,1]
	v_mul_f32_e32 v12, 0xbd38aa3b, v78
	v_exp_f32_e32 v12, v12
	v_lshl_add_u64 v[8:9], v[8:9], 0, v[2:3]
	global_store_dword v[8:9], v11, off
	global_store_dword v[8:9], v7, off offset:64
	v_add_f32_e32 v8, 1.0, v12
	v_mul_f32_e32 v11, 0xbd38aa3b, v79
	v_rcp_f32_e32 v8, v8
	v_exp_f32_e32 v11, v11
	v_mul_f32_e32 v14, 0x3d000000, v76
	v_mul_f32_e32 v8, v78, v8
	v_add_f32_e32 v10, 1.0, v11
	v_rcp_f32_e32 v10, v10
	v_mul_f32_e32 v8, v74, v8
	v_mul_f32_e32 v8, 0x3b800000, v8
	v_med3_f32 v11, v8, s55, v197
	v_mul_f32_e32 v9, v79, v10
	v_mul_f32_e32 v12, 0xbd38aa3b, v80
	v_exp_f32_e32 v12, v12
	v_mul_f32_e32 v8, v75, v9
	v_mul_f32_e32 v8, 0x3b800000, v8
	v_add_f32_e32 v9, 1.0, v12
	v_mul_f32_e32 v13, 0xbd38aa3b, v81
	v_rcp_f32_e32 v9, v9
	v_exp_f32_e32 v13, v13
	v_med3_f32 v8, v8, s55, v197
	v_cvt_pk_fp8_f32 v11, v11, v8
	v_mul_f32_e32 v9, v80, v9
	v_add_f32_e32 v10, 1.0, v13
	v_rcp_f32_e32 v10, v10
	v_mul_f32_e32 v9, v76, v9
	v_mul_f32_e32 v9, 0x3b800000, v9
	v_mul_f32_e32 v10, v81, v10
	v_mul_f32_e32 v8, v77, v10
	v_mul_f32_e32 v8, 0x3b800000, v8
	v_med3_f32 v9, v9, s55, v197
	v_med3_f32 v8, v8, s55, v197
	v_cvt_pk_fp8_f32 v11, v9, v8 op_sel:[0,0,1]
	v_mul_f32_e32 v8, 0xbd38aa3b, v70
	v_exp_f32_e32 v12, v8
	v_add_u32_e32 v7, 0x80, v6
	v_mad_i64_i32 v[8:9], s[24:25], v7, s58, v[4:5]
	v_add_f32_e32 v7, 1.0, v12
	v_mul_f32_e32 v12, 0x3d000000, v71
	v_mul_f32_e32 v13, 0xbd38aa3b, v71
	v_rcp_f32_e32 v7, v7
	v_exp_f32_e32 v13, v13
	v_mul_f32_e32 v16, 0x3d000000, v68
	v_mul_f32_e32 v7, v70, v7
	v_add_f32_e32 v10, 1.0, v13
	v_rcp_f32_e32 v10, v10
	v_mul_f32_e32 v7, v66, v7
	v_mul_f32_e32 v7, 0x3b800000, v7
	v_mul_f32_e32 v10, v71, v10
	v_mul_f32_e32 v14, 0xbd38aa3b, v72
	v_exp_f32_e32 v14, v14
	v_mul_f32_e32 v10, v67, v10
	v_mul_f32_e32 v10, 0x3b800000, v10
	v_med3_f32 v7, v7, s55, v197
	v_add_f32_e32 v13, 1.0, v14
	v_mul_f32_e32 v14, 0x3d000000, v73
	v_mul_f32_e32 v15, 0xbd38aa3b, v73
	v_rcp_f32_e32 v13, v13
	v_exp_f32_e32 v15, v15
	v_med3_f32 v10, v10, s55, v197
	v_cvt_pk_fp8_f32 v7, v7, v10
	v_mul_f32_e32 v12, v72, v13
	v_add_f32_e32 v13, 1.0, v15
	v_rcp_f32_e32 v13, v13
	v_mul_f32_e32 v12, v68, v12
	v_mul_f32_e32 v12, 0x3b800000, v12
	v_mul_f32_e32 v13, v73, v13
	v_mul_f32_e32 v10, v69, v13
	v_mul_f32_e32 v10, 0x3b800000, v10
	v_med3_f32 v12, v12, s55, v197
	v_med3_f32 v10, v10, s55, v197
	v_cvt_pk_fp8_f32 v7, v12, v10 op_sel:[0,0,1]
	v_mul_f32_e32 v12, 0xbd38aa3b, v62
	v_exp_f32_e32 v12, v12
	v_lshl_add_u64 v[8:9], v[8:9], 0, v[2:3]
	global_store_dword v[8:9], v11, off
	global_store_dword v[8:9], v7, off offset:64
	v_add_f32_e32 v8, 1.0, v12
	v_mul_f32_e32 v11, 0xbd38aa3b, v63
	v_rcp_f32_e32 v8, v8
	v_exp_f32_e32 v11, v11
	v_mul_f32_e32 v14, 0x3d000000, v60
	v_mul_f32_e32 v8, v62, v8
	v_add_f32_e32 v10, 1.0, v11
	v_rcp_f32_e32 v10, v10
	v_mul_f32_e32 v8, v58, v8
	v_mul_f32_e32 v8, 0x3b800000, v8
	v_med3_f32 v11, v8, s55, v197
	v_mul_f32_e32 v9, v63, v10
	v_mul_f32_e32 v12, 0xbd38aa3b, v64
	v_exp_f32_e32 v12, v12
	v_mul_f32_e32 v8, v59, v9
	v_mul_f32_e32 v8, 0x3b800000, v8
	v_add_f32_e32 v9, 1.0, v12
	v_mul_f32_e32 v13, 0xbd38aa3b, v65
	v_rcp_f32_e32 v9, v9
	v_exp_f32_e32 v13, v13
	v_med3_f32 v8, v8, s55, v197
	v_cvt_pk_fp8_f32 v11, v11, v8
	v_mul_f32_e32 v9, v64, v9
	v_add_f32_e32 v10, 1.0, v13
	v_rcp_f32_e32 v10, v10
	v_mul_f32_e32 v9, v60, v9
	v_mul_f32_e32 v9, 0x3b800000, v9
	v_mul_f32_e32 v10, v65, v10
	v_mul_f32_e32 v8, v61, v10
	v_mul_f32_e32 v8, 0x3b800000, v8
	v_med3_f32 v9, v9, s55, v197
	v_med3_f32 v8, v8, s55, v197
	v_cvt_pk_fp8_f32 v11, v9, v8 op_sel:[0,0,1]
	v_mul_f32_e32 v8, 0xbd38aa3b, v54
	v_exp_f32_e32 v12, v8
	v_add_u32_e32 v7, 0x90, v6
	v_mad_i64_i32 v[8:9], s[24:25], v7, s58, v[4:5]
	v_add_f32_e32 v7, 1.0, v12
	v_mul_f32_e32 v12, 0x3d000000, v55
	v_mul_f32_e32 v13, 0xbd38aa3b, v55
	v_rcp_f32_e32 v7, v7
	v_exp_f32_e32 v13, v13
	v_mul_f32_e32 v16, 0x3d000000, v52
	v_mul_f32_e32 v7, v54, v7
	v_add_f32_e32 v10, 1.0, v13
	v_rcp_f32_e32 v10, v10
	v_mul_f32_e32 v7, v50, v7
	v_mul_f32_e32 v7, 0x3b800000, v7
	v_mul_f32_e32 v10, v55, v10
	v_mul_f32_e32 v14, 0xbd38aa3b, v56
	v_exp_f32_e32 v14, v14
	v_mul_f32_e32 v10, v51, v10
	v_mul_f32_e32 v10, 0x3b800000, v10
	v_med3_f32 v7, v7, s55, v197
	v_add_f32_e32 v13, 1.0, v14
	v_mul_f32_e32 v14, 0x3d000000, v57
	v_mul_f32_e32 v15, 0xbd38aa3b, v57
	v_rcp_f32_e32 v13, v13
	v_exp_f32_e32 v15, v15
	v_med3_f32 v10, v10, s55, v197
	v_cvt_pk_fp8_f32 v7, v7, v10
	v_mul_f32_e32 v12, v56, v13
	v_add_f32_e32 v13, 1.0, v15
	v_rcp_f32_e32 v13, v13
	v_mul_f32_e32 v12, v52, v12
	v_mul_f32_e32 v12, 0x3b800000, v12
	v_mul_f32_e32 v13, v57, v13
	v_mul_f32_e32 v10, v53, v13
	v_mul_f32_e32 v10, 0x3b800000, v10
	v_med3_f32 v12, v12, s55, v197
	v_med3_f32 v10, v10, s55, v197
	v_cvt_pk_fp8_f32 v7, v12, v10 op_sel:[0,0,1]
	v_mul_f32_e32 v12, 0xbd38aa3b, v46
	v_exp_f32_e32 v12, v12
	v_lshl_add_u64 v[8:9], v[8:9], 0, v[2:3]
	global_store_dword v[8:9], v11, off
	global_store_dword v[8:9], v7, off offset:64
	v_add_f32_e32 v8, 1.0, v12
	v_mul_f32_e32 v11, 0xbd38aa3b, v47
	v_rcp_f32_e32 v8, v8
	v_exp_f32_e32 v11, v11
	v_mul_f32_e32 v14, 0x3d000000, v44
	v_mul_f32_e32 v8, v46, v8
	v_add_f32_e32 v10, 1.0, v11
	v_rcp_f32_e32 v10, v10
	v_mul_f32_e32 v8, v42, v8
	v_mul_f32_e32 v8, 0x3b800000, v8
	v_med3_f32 v11, v8, s55, v197
	v_mul_f32_e32 v9, v47, v10
	v_mul_f32_e32 v12, 0xbd38aa3b, v48
	v_exp_f32_e32 v12, v12
	v_mul_f32_e32 v8, v43, v9
	v_mul_f32_e32 v8, 0x3b800000, v8
	v_add_f32_e32 v9, 1.0, v12
	v_mul_f32_e32 v13, 0xbd38aa3b, v49
	v_rcp_f32_e32 v9, v9
	v_exp_f32_e32 v13, v13
	v_med3_f32 v8, v8, s55, v197
	v_cvt_pk_fp8_f32 v11, v11, v8
	v_mul_f32_e32 v9, v48, v9
	v_add_f32_e32 v10, 1.0, v13
	v_rcp_f32_e32 v10, v10
	v_mul_f32_e32 v9, v44, v9
	v_mul_f32_e32 v9, 0x3b800000, v9
	v_mul_f32_e32 v10, v49, v10
	v_mul_f32_e32 v8, v45, v10
	v_mul_f32_e32 v8, 0x3b800000, v8
	v_med3_f32 v9, v9, s55, v197
	v_med3_f32 v8, v8, s55, v197
	v_cvt_pk_fp8_f32 v11, v9, v8 op_sel:[0,0,1]
	v_mul_f32_e32 v8, 0xbd38aa3b, v38
	v_exp_f32_e32 v12, v8
	v_add_u32_e32 v7, 0xa0, v6
	v_mad_i64_i32 v[8:9], s[24:25], v7, s58, v[4:5]
	v_add_f32_e32 v7, 1.0, v12
	v_mul_f32_e32 v12, 0x3d000000, v39
	v_mul_f32_e32 v13, 0xbd38aa3b, v39
	v_rcp_f32_e32 v7, v7
	v_exp_f32_e32 v13, v13
	v_mul_f32_e32 v7, v38, v7
	v_add_f32_e32 v10, 1.0, v13
	v_rcp_f32_e32 v10, v10
	v_mul_f32_e32 v7, v34, v7
	v_mul_f32_e32 v7, 0x3b800000, v7
	v_mul_f32_e32 v10, v39, v10
	v_mul_f32_e32 v14, 0xbd38aa3b, v40
	v_exp_f32_e32 v14, v14
	v_mul_f32_e32 v10, v35, v10
	v_mul_f32_e32 v10, 0x3b800000, v10
	v_med3_f32 v7, v7, s55, v197
	v_add_f32_e32 v13, 1.0, v14
	v_mul_f32_e32 v14, 0x3d000000, v41
	v_mul_f32_e32 v15, 0xbd38aa3b, v41
	v_rcp_f32_e32 v13, v13
	v_exp_f32_e32 v15, v15
	v_med3_f32 v10, v10, s55, v197
	v_cvt_pk_fp8_f32 v7, v7, v10
	v_mul_f32_e32 v12, v40, v13
	v_add_f32_e32 v13, 1.0, v15
	v_rcp_f32_e32 v13, v13
	v_mul_f32_e32 v12, v36, v12
	v_mul_f32_e32 v12, 0x3b800000, v12
	v_mul_f32_e32 v13, v41, v13
	v_mul_f32_e32 v10, v37, v13
	v_mul_f32_e32 v10, 0x3b800000, v10
	v_med3_f32 v12, v12, s55, v197
	v_med3_f32 v10, v10, s55, v197
	v_cvt_pk_fp8_f32 v7, v12, v10 op_sel:[0,0,1]
	v_lshl_add_u64 v[8:9], v[8:9], 0, v[2:3]
	v_mul_f32_e32 v10, 0x3d000000, v30
	global_store_dword v[8:9], v11, off
	global_store_dword v[8:9], v7, off offset:64
	v_mul_f32_e32 v12, 0xbd38aa3b, v30
	v_mul_f32_e32 v9, 0xbd38aa3b, v31
	v_exp_f32_e32 v12, v12
	v_exp_f32_e32 v9, v9
	v_add_f32_e32 v7, 1.0, v12
	v_add_f32_e32 v9, 1.0, v9
	v_rcp_f32_e32 v7, v7
	v_rcp_f32_e32 v9, v9
	v_add_u32_e32 v6, 0xb0, v6
	v_mul_f32_e32 v7, v30, v7
	v_mul_f32_e32 v8, v31, v9
	v_mul_f32_e32 v7, v26, v7
	v_mul_f32_e32 v11, 0xbd38aa3b, v32
	v_exp_f32_e32 v11, v11
	v_mul_f32_e32 v8, v27, v8
	v_mul_f32_e32 v7, 0x3b800000, v7
	v_add_f32_e32 v10, 1.0, v11
	v_mul_f32_e32 v12, 0xbd38aa3b, v33
	v_rcp_f32_e32 v10, v10
	v_exp_f32_e32 v12, v12
	v_mul_f32_e32 v8, 0x3b800000, v8
	v_med3_f32 v7, v7, s55, v197
	v_mul_f32_e32 v9, v32, v10
	v_add_f32_e32 v10, 1.0, v12
	v_rcp_f32_e32 v10, v10
	v_med3_f32 v8, v8, s55, v197
	v_cvt_pk_fp8_f32 v7, v7, v8
	v_mul_f32_e32 v12, 0x3d000000, v29
	v_mul_f32_e32 v10, v33, v10
	v_mul_f32_e32 v11, 0xbd38aa3b, v22
	v_mul_f32_e32 v9, v28, v9
	v_mul_f32_e32 v10, v29, v10
	v_exp_f32_e32 v11, v11
	v_mul_f32_e32 v9, 0x3b800000, v9
	v_mul_f32_e32 v10, 0x3b800000, v10
	v_med3_f32 v9, v9, s55, v197
	v_med3_f32 v10, v10, s55, v197
	v_cvt_pk_fp8_f32 v7, v9, v10 op_sel:[0,0,1]
	v_mul_f32_e32 v10, 0x3d000000, v23
	v_add_f32_e32 v9, 1.0, v11
	v_mul_f32_e32 v11, 0xbd38aa3b, v23
	v_rcp_f32_e32 v9, v9
	v_exp_f32_e32 v11, v11
	v_mad_i64_i32 v[4:5], s[24:25], v6, s58, v[4:5]
	v_mul_f32_e32 v8, v22, v9
	v_add_f32_e32 v9, 1.0, v11
	v_rcp_f32_e32 v9, v9
	v_mul_f32_e32 v8, v18, v8
	v_mul_f32_e32 v8, 0x3b800000, v8
	v_mul_f32_e32 v9, v23, v9
	v_mul_f32_e32 v12, 0xbd38aa3b, v24
	v_exp_f32_e32 v12, v12
	v_mul_f32_e32 v9, v19, v9
	v_mul_f32_e32 v9, 0x3b800000, v9
	v_med3_f32 v8, v8, s55, v197
	v_add_f32_e32 v11, 1.0, v12
	v_mul_f32_e32 v13, 0xbd38aa3b, v25
	v_rcp_f32_e32 v11, v11
	v_exp_f32_e32 v13, v13
	v_med3_f32 v9, v9, s55, v197
	v_cvt_pk_fp8_f32 v8, v8, v9
	v_mul_f32_e32 v10, v24, v11
	v_add_f32_e32 v11, 1.0, v13
	v_rcp_f32_e32 v11, v11
	v_mul_f32_e32 v10, v20, v10
	v_mul_f32_e32 v10, 0x3b800000, v10
	v_mul_f32_e32 v11, v25, v11
	v_mul_f32_e32 v9, v21, v11
	v_mul_f32_e32 v9, 0x3b800000, v9
	v_med3_f32 v10, v10, s55, v197
	v_med3_f32 v9, v9, s55, v197
	v_cvt_pk_fp8_f32 v8, v10, v9 op_sel:[0,0,1]
	v_lshl_add_u64 v[2:3], v[4:5], 0, v[2:3]
	v_mov_b32_e32 v200, v161
	v_mov_b32_e32 v158, v163
	v_mov_b32_e32 v160, v198
	v_mov_b32_e32 v162, v199
	s_mov_b32 s22, s18
	s_mov_b32 s60, s59
	s_mov_b64 s[24:25], s[20:21]
	global_store_dword v[2:3], v7, off
	global_store_dword v[2:3], v8, off offset:64
	s_cbranch_vccz .LBB0_5613
	s_waitcnt vmcnt(0)
	s_cmpk_gt_u32 s31, 0xff
	s_cbranch_scc1 .LBB0_5620
	s_barrier

.LBB0_5680:
	s_add_u32 s14, s10, 0x1ffae100
	s_addc_u32 s15, s11, 0
	s_add_u32 s16, s10, 0x1fb5d100
	s_addc_u32 s17, s11, 0
	s_lshl_b32 s1, s8, 5
	s_add_i32 s50, s41, 0x18000
	s_mov_b64 s[18:19], 0x80
	s_and_b32 s1, s1, 0x60
	v_lshl_add_u64 v[8:9], v[8:9], 0, s[18:19]
	s_mov_b32 m0, s50
	s_add_i32 s51, s41, 0x1a000
	s_lshl_b32 s0, s7, 13
	s_lshl_b32 s2, s1, 7
	s_waitcnt vmcnt(0)
	s_barrier
	global_load_lds_dwordx4 v[8:9], off
	v_lshl_add_u64 v[6:7], v[6:7], 0, s[18:19]
	s_mov_b32 m0, s51
	s_add_i32 s52, s41, 0x8000
	s_add_i32 s53, s41, 0xa000
	global_load_lds_dwordx4 v[6:7], off
	v_lshl_add_u64 v[4:5], v[4:5], 0, s[18:19]
	s_mov_b32 m0, s52
	s_add_u32 s8, s28, 0x58080
	global_load_lds_dwordx4 v[4:5], off
	v_lshl_add_u64 v[2:3], v[2:3], 0, s[18:19]
	s_mov_b32 m0, s53
	s_addc_u32 s9, s29, 0
	s_add_i32 s55, s41, 0x1c000
	global_load_lds_dwordx4 v[2:3], off
	v_lshl_add_u64 v[2:3], s[8:9], 0, v[146:147]
	s_mov_b32 m0, s55
	s_add_i32 s58, s41, 0x1e000
	global_load_lds_dwordx4 v[2:3], off
	v_lshl_add_u64 v[2:3], s[8:9], 0, v[148:149]
	s_mov_b32 m0, s58
	v_lshlrev_b32_e32 v5, 2, v10
	global_load_lds_dwordx4 v[2:3], off
	v_and_b32_e32 v2, 15, v10
	v_bfe_u32 v3, v10, 4, 2
	v_lshl_or_b32 v166, s7, 6, v2
	v_lshlrev_b32_e32 v4, 4, v3
	v_lshlrev_b32_e32 v2, 6, v2
	v_and_b32_e32 v5, 32, v5
	v_bitop3_b32 v2, v2, v5, v4 bitop3:0x36
	s_add_i32 s2, s2, 0
	v_add_u32_e32 v4, s2, v2
	v_add_u32_e32 v5, 0, v2
	v_lshl_or_b32 v183, v3, 2, s1
	v_lshrrev_b32_e32 v3, 1, v15
	v_mul_lo_u32 v2, v17, s6
	s_movk_i32 s1, 0x5800
	v_mad_u64_u32 v[2:3], s[10:11], v3, s1, v[2:3]
	v_or_b32_e32 v2, v2, v16
	s_mov_b64 s[8:9], 0x58080
	v_add_lshl_u32 v2, v2, v18, 1
	v_mov_b32_e32 v3, v147
	v_lshl_add_u64 v[150:151], v[2:3], 0, s[8:9]
	v_lshrrev_b32_e32 v3, 1, v11
	v_mul_lo_u32 v2, v12, s6
	v_mad_u64_u32 v[2:3], s[6:7], v3, s1, v[2:3]
	s_waitcnt vmcnt(6)
	v_or_b32_e32 v2, v2, v13
	v_readlane_b32 s2, v252, 8
	v_add_lshl_u32 v2, v2, v14, 1
	v_mov_b32_e32 v3, v147
	v_add_u32_e32 v167, 0x10000, v4
	v_add_u32_e32 v168, 0x14000, v4
	v_add_u32_e32 v169, 0x18000, v4
	v_add_u32_e32 v170, 0x1c000, v4
	v_add_u32_e32 v171, 0x10400, v4
	v_add_u32_e32 v172, 0x10800, v4
	v_add_u32_e32 v173, 0x10c00, v4
	v_add_u32_e32 v174, 0x14400, v4
	v_add_u32_e32 v175, 0x14800, v4
	v_add_u32_e32 v176, 0x14c00, v4
	v_add_u32_e32 v177, 0x18400, v4
	v_add_u32_e32 v178, 0x18800, v4
	v_add_u32_e32 v179, 0x18c00, v4
	v_add_u32_e32 v180, 0x1c400, v4
	v_add_u32_e32 v181, 0x1c800, v4
	v_add_u32_e32 v182, 0x1cc00, v4
	s_ashr_i32 s59, s2, 31
	v_lshl_add_u64 v[152:153], v[2:3], 0, s[8:9]
	v_mov_b64_e32 v[154:155], 0x400
	v_mov_b64_e32 v[156:157], 0x3ff
	v_add_u32_e32 v184, s0, v5
	s_mov_b64 s[20:21], 0x40000
	s_mov_b32 s60, 0x40000
	s_mov_b64 s[22:23], 0x48000
	s_mov_b32 s61, 0x48000
	s_mov_b64 s[24:25], 0x50000
	s_mov_b32 s62, 0x50000
	s_mov_b32 s63, 0x58000
	s_barrier

.LBB0_5692:
	ds_read_b128 v[2:5], v167
	ds_read_b128 v[6:9], v171
	ds_read_b128 v[10:13], v172
	ds_read_b128 v[14:17], v173
	s_add_u32 s28, s26, 0x100
	s_addc_u32 s29, s27, 0
	s_cmp_eq_u32 s70, 18
	s_cselect_b32 s35, s9, s29
	s_cselect_b32 s34, s8, s28
	s_cselect_b32 s31, s11, s69
	s_cselect_b32 s30, s10, s68
	v_lshl_add_u64 v[158:159], s[26:27], 0, v[152:153]
	s_add_i32 m0, s41, 0xc000
	ds_read_b128 v[186:189], v184
	ds_read_b128 v[190:193], v184 offset:1024
	ds_read_b128 v[194:197], v184 offset:2048
	ds_read_b128 v[198:201], v184 offset:3072
	ds_read_b128 v[202:205], v184 offset:4096
	ds_read_b128 v[206:209], v184 offset:5120
	ds_read_b128 v[210:213], v184 offset:6144
	ds_read_b128 v[214:217], v184 offset:7168
	global_load_lds_dwordx4 v[158:159], off
	v_lshl_add_u64 v[158:159], s[26:27], 0, v[150:151]
	s_add_i32 m0, s41, 0xe000
	s_nop 0
	global_load_lds_dwordx4 v[158:159], off
	ds_read_b128 v[220:223], v168
	ds_read_b128 v[224:227], v174
	ds_read_b128 v[228:231], v175
	ds_read_b128 v[232:235], v176
	s_waitcnt lgkmcnt(0)
	s_barrier
	s_waitcnt lgkmcnt(0)
	s_setprio 1
	s_waitcnt lgkmcnt(0)
	v_mfma_f32_16x16x128_f8f6f4 v[142:145], v[2:9], v[186:193], v[142:145]
	v_mfma_f32_16x16x128_f8f6f4 v[138:141], v[10:17], v[186:193], v[138:141]
	v_mfma_f32_16x16x128_f8f6f4 v[134:137], v[2:9], v[194:201], v[134:137]
	v_mfma_f32_16x16x128_f8f6f4 v[130:133], v[10:17], v[194:201], v[130:133]
	v_mfma_f32_16x16x128_f8f6f4 v[110:113], v[2:9], v[202:209], v[110:113]
	v_mfma_f32_16x16x128_f8f6f4 v[106:109], v[10:17], v[202:209], v[106:109]
	v_mfma_f32_16x16x128_f8f6f4 v[102:105], v[2:9], v[210:217], v[102:105]
	v_mfma_f32_16x16x128_f8f6f4 v[98:101], v[10:17], v[210:217], v[98:101]
	s_setprio 0
	s_waitcnt lgkmcnt(0)
	s_setprio 1
	s_waitcnt lgkmcnt(0)
	v_mfma_f32_16x16x128_f8f6f4 v[126:129], v[220:227], v[186:193], v[126:129]
	v_mfma_f32_16x16x128_f8f6f4 v[122:125], v[228:235], v[186:193], v[122:125]
	v_mfma_f32_16x16x128_f8f6f4 v[118:121], v[220:227], v[194:201], v[118:121]
	v_mfma_f32_16x16x128_f8f6f4 v[114:117], v[228:235], v[194:201], v[114:117]
	v_mfma_f32_16x16x128_f8f6f4 v[94:97], v[220:227], v[202:209], v[94:97]
	v_mfma_f32_16x16x128_f8f6f4 v[90:93], v[228:235], v[202:209], v[90:93]
	v_mfma_f32_16x16x128_f8f6f4 v[86:89], v[220:227], v[210:217], v[86:89]
	v_mfma_f32_16x16x128_f8f6f4 v[82:85], v[228:235], v[210:217], v[82:85]
	s_setprio 0
	s_barrier
	s_mov_b32 m0, s42
	v_lshl_add_u64 v[158:159], s[30:31], 0, v[146:147]
	global_load_lds_dwordx4 v[158:159], off
	v_lshl_add_u64 v[160:161], s[30:31], 0, v[148:149]
	s_mov_b32 m0, s43
	s_nop 0
	global_load_lds_dwordx4 v[160:161], off
	s_mov_b32 m0, s41
	v_lshl_add_u64 v[162:163], s[34:35], 0, v[146:147]
	ds_read_b128 v[186:189], v184 offset:16384
	ds_read_b128 v[190:193], v184 offset:17408
	ds_read_b128 v[194:197], v184 offset:18432
	ds_read_b128 v[198:201], v184 offset:19456
	ds_read_b128 v[202:205], v184 offset:20480
	ds_read_b128 v[206:209], v184 offset:21504
	ds_read_b128 v[210:213], v184 offset:22528
	ds_read_b128 v[214:217], v184 offset:23552
	global_load_lds_dwordx4 v[162:163], off
	v_lshl_add_u64 v[164:165], s[34:35], 0, v[148:149]
	s_mov_b32 m0, s44
	s_nop 0
	global_load_lds_dwordx4 v[164:165], off
	s_add_u32 s26, s30, 0x58000
	s_addc_u32 s27, s31, 0
	s_mov_b32 m0, s45
	v_lshl_add_u64 v[254:255], s[26:27], 0, v[146:147]
	global_load_lds_dwordx4 v[254:255], off
	v_lshl_add_u64 v[254:255], s[26:27], 0, v[148:149]
	s_mov_b32 m0, s46
	s_nop 0
	global_load_lds_dwordx4 v[254:255], off
	s_waitcnt vmcnt(6)
	s_waitcnt lgkmcnt(0)
	s_barrier
	s_waitcnt lgkmcnt(0)
	s_setprio 1
	s_waitcnt lgkmcnt(0)
	v_mfma_f32_16x16x128_f8f6f4 v[78:81], v[2:9], v[186:193], v[78:81]
	v_mfma_f32_16x16x128_f8f6f4 v[74:77], v[10:17], v[186:193], v[74:77]
	v_mfma_f32_16x16x128_f8f6f4 v[70:73], v[2:9], v[194:201], v[70:73]
	v_mfma_f32_16x16x128_f8f6f4 v[66:69], v[10:17], v[194:201], v[66:69]
	v_mfma_f32_16x16x128_f8f6f4 v[46:49], v[2:9], v[202:209], v[46:49]
	v_mfma_f32_16x16x128_f8f6f4 v[42:45], v[10:17], v[202:209], v[42:45]
	v_mfma_f32_16x16x128_f8f6f4 v[38:41], v[2:9], v[210:217], v[38:41]
	v_mfma_f32_16x16x128_f8f6f4 v[34:37], v[10:17], v[210:217], v[34:37]
	s_setprio 0
	s_setprio 1
	v_mfma_f32_16x16x128_f8f6f4 v[62:65], v[220:227], v[186:193], v[62:65]
	v_mfma_f32_16x16x128_f8f6f4 v[58:61], v[228:235], v[186:193], v[58:61]
	v_mfma_f32_16x16x128_f8f6f4 v[54:57], v[220:227], v[194:201], v[54:57]
	v_mfma_f32_16x16x128_f8f6f4 v[50:53], v[228:235], v[194:201], v[50:53]
	v_mfma_f32_16x16x128_f8f6f4 v[30:33], v[220:227], v[202:209], v[30:33]
	v_mfma_f32_16x16x128_f8f6f4 v[26:29], v[228:235], v[202:209], v[26:29]
	v_mfma_f32_16x16x128_f8f6f4 v[22:25], v[220:227], v[210:217], v[22:25]
	v_mfma_f32_16x16x128_f8f6f4 v[18:21], v[228:235], v[210:217], v[18:21]
	s_setprio 0
	s_barrier
	ds_read_b128 v[2:5], v169
	ds_read_b128 v[6:9], v177
	ds_read_b128 v[10:13], v178
	ds_read_b128 v[14:17], v179
	s_add_u32 s26, s34, 0x58000
	s_addc_u32 s27, s35, 0
	s_mov_b32 m0, s47
	v_lshl_add_u64 v[220:221], s[26:27], 0, v[146:147]
	ds_read_b128 v[186:189], v184 offset:32768
	ds_read_b128 v[190:193], v184 offset:33792
	ds_read_b128 v[194:197], v184 offset:34816
	ds_read_b128 v[198:201], v184 offset:35840
	ds_read_b128 v[202:205], v184 offset:36864
	ds_read_b128 v[206:209], v184 offset:37888
	ds_read_b128 v[210:213], v184 offset:38912
	ds_read_b128 v[214:217], v184 offset:39936
	global_load_lds_dwordx4 v[220:221], off
	v_lshl_add_u64 v[220:221], s[26:27], 0, v[148:149]
	s_mov_b32 m0, s48
	s_nop 0
	global_load_lds_dwordx4 v[220:221], off
	ds_read_b128 v[220:223], v170
	ds_read_b128 v[224:227], v180
	ds_read_b128 v[228:231], v181
	ds_read_b128 v[232:235], v182
	s_waitcnt lgkmcnt(0)
	s_barrier
	s_waitcnt lgkmcnt(0)
	s_setprio 1
	s_waitcnt lgkmcnt(0)
	v_mfma_f32_16x16x128_f8f6f4 v[142:145], v[2:9], v[186:193], v[142:145]
	v_mfma_f32_16x16x128_f8f6f4 v[138:141], v[10:17], v[186:193], v[138:141]
	v_mfma_f32_16x16x128_f8f6f4 v[134:137], v[2:9], v[194:201], v[134:137]
	v_mfma_f32_16x16x128_f8f6f4 v[130:133], v[10:17], v[194:201], v[130:133]
	v_mfma_f32_16x16x128_f8f6f4 v[110:113], v[2:9], v[202:209], v[110:113]
	v_mfma_f32_16x16x128_f8f6f4 v[106:109], v[10:17], v[202:209], v[106:109]
	v_mfma_f32_16x16x128_f8f6f4 v[102:105], v[2:9], v[210:217], v[102:105]
	v_mfma_f32_16x16x128_f8f6f4 v[98:101], v[10:17], v[210:217], v[98:101]
	s_setprio 0
	s_waitcnt lgkmcnt(0)
	s_setprio 1
	s_waitcnt lgkmcnt(0)
	v_mfma_f32_16x16x128_f8f6f4 v[126:129], v[220:227], v[186:193], v[126:129]
	v_mfma_f32_16x16x128_f8f6f4 v[122:125], v[228:235], v[186:193], v[122:125]
	v_mfma_f32_16x16x128_f8f6f4 v[118:121], v[220:227], v[194:201], v[118:121]
	v_mfma_f32_16x16x128_f8f6f4 v[114:117], v[228:235], v[194:201], v[114:117]
	v_mfma_f32_16x16x128_f8f6f4 v[94:97], v[220:227], v[202:209], v[94:97]
	v_mfma_f32_16x16x128_f8f6f4 v[90:93], v[228:235], v[202:209], v[90:93]
	v_mfma_f32_16x16x128_f8f6f4 v[86:89], v[220:227], v[210:217], v[86:89]
	v_mfma_f32_16x16x128_f8f6f4 v[82:85], v[228:235], v[210:217], v[82:85]
	s_setprio 0
	s_barrier
	s_mov_b32 m0, s50
	v_lshl_add_u64 v[158:159], v[158:159], 0, s[18:19]
	global_load_lds_dwordx4 v[158:159], off
	v_lshl_add_u64 v[158:159], v[160:161], 0, s[18:19]
	s_mov_b32 m0, s51
	s_nop 0
	global_load_lds_dwordx4 v[158:159], off
	s_mov_b32 m0, s52
	v_lshl_add_u64 v[158:159], v[162:163], 0, s[18:19]
	ds_read_b128 v[186:189], v184 offset:49152
	ds_read_b128 v[190:193], v184 offset:50176
	ds_read_b128 v[194:197], v184 offset:51200
	ds_read_b128 v[198:201], v184 offset:52224
	ds_read_b128 v[202:205], v184 offset:53248
	ds_read_b128 v[206:209], v184 offset:54272
	ds_read_b128 v[210:213], v184 offset:55296
	ds_read_b128 v[214:217], v184 offset:56320
	global_load_lds_dwordx4 v[158:159], off
	v_lshl_add_u64 v[158:159], v[164:165], 0, s[18:19]
	s_mov_b32 m0, s53
	s_nop 0
	global_load_lds_dwordx4 v[158:159], off
	s_add_u32 s26, s30, 0x58080
	s_addc_u32 s27, s31, 0
	s_mov_b32 m0, s55
	v_lshl_add_u64 v[254:255], s[26:27], 0, v[146:147]
	global_load_lds_dwordx4 v[254:255], off
	v_lshl_add_u64 v[254:255], s[26:27], 0, v[148:149]
	s_mov_b32 m0, s58
	s_nop 0
	global_load_lds_dwordx4 v[254:255], off
	s_waitcnt vmcnt(6)
	s_waitcnt lgkmcnt(0)
	s_barrier
	s_waitcnt lgkmcnt(0)
	s_setprio 1
	s_waitcnt lgkmcnt(0)
	v_mfma_f32_16x16x128_f8f6f4 v[78:81], v[2:9], v[186:193], v[78:81]
	v_mfma_f32_16x16x128_f8f6f4 v[74:77], v[10:17], v[186:193], v[74:77]
	v_mfma_f32_16x16x128_f8f6f4 v[70:73], v[2:9], v[194:201], v[70:73]
	v_mfma_f32_16x16x128_f8f6f4 v[66:69], v[10:17], v[194:201], v[66:69]
	v_mfma_f32_16x16x128_f8f6f4 v[46:49], v[2:9], v[202:209], v[46:49]
	v_mfma_f32_16x16x128_f8f6f4 v[42:45], v[10:17], v[202:209], v[42:45]
	v_mfma_f32_16x16x128_f8f6f4 v[38:41], v[2:9], v[210:217], v[38:41]
	v_mfma_f32_16x16x128_f8f6f4 v[34:37], v[10:17], v[210:217], v[34:37]
	s_setprio 0
	s_setprio 1
	v_mfma_f32_16x16x128_f8f6f4 v[62:65], v[220:227], v[186:193], v[62:65]
	v_mfma_f32_16x16x128_f8f6f4 v[58:61], v[228:235], v[186:193], v[58:61]
	v_mfma_f32_16x16x128_f8f6f4 v[54:57], v[220:227], v[194:201], v[54:57]
	v_mfma_f32_16x16x128_f8f6f4 v[50:53], v[228:235], v[194:201], v[50:53]
	v_mfma_f32_16x16x128_f8f6f4 v[30:33], v[220:227], v[202:209], v[30:33]
	v_mfma_f32_16x16x128_f8f6f4 v[26:29], v[228:235], v[202:209], v[26:29]
	v_mfma_f32_16x16x128_f8f6f4 v[22:25], v[220:227], v[210:217], v[22:25]
	v_mfma_f32_16x16x128_f8f6f4 v[18:21], v[228:235], v[210:217], v[18:21]
	s_setprio 0
	s_add_i32 s70, s70, 2
	s_add_u32 s68, s68, 0x100
	s_addc_u32 s69, s69, 0
	s_cmp_gt_u32 s70, 19
	s_mov_b64 s[26:27], s[28:29]
	s_barrier
	s_cbranch_scc0 .LBB0_5692
	v_bfe_u32 v160, v0, 4, 1
	v_mul_u32_u24_e32 v160, 24, v160
	v_mov_b32_e32 v161, 0
	v_lshl_add_u32 v6, s67, 8, v166
	v_ashrrev_i32_e32 v7, 31, v6
	v_or_b32_e32 v4, 16, v6
	s_nop 15
	s_nop 15
	v_lshl_add_u64 v[2:3], v[6:7], 2, s[16:17]
	v_ashrrev_i32_e32 v5, 31, v4
	global_load_dword v158, v[2:3], off
	v_lshl_add_u64 v[8:9], v[4:5], 2, s[16:17]
	global_load_dword v159, v[8:9], off
	s_ashr_i32 s0, s66, 31
	s_lshr_b32 s0, s0, 30
	s_add_i32 s0, s66, s0
	s_and_b32 s0, s0, 0xfffffc
	v_lshlrev_b64 v[4:5], 11, v[4:5]
	s_sub_i32 s0, s66, s0
	v_lshl_add_u64 v[14:15], s[14:15], 0, v[4:5]
	v_lshl_or_b32 v4, s0, 8, v183
	v_lshlrev_b64 v[10:11], 11, v[6:7]
	v_ashrrev_i32_e32 v5, 31, v4
	v_lshl_add_u64 v[10:11], s[14:15], 0, v[10:11]
	v_lshlrev_b64 v[16:17], 1, v[4:5]
	v_lshl_add_u64 v[4:5], v[10:11], 0, v[16:17]
	v_lshl_add_u64 v[10:11], v[14:15], 0, v[16:17]
	v_or_b32_e32 v8, 32, v6
	v_ashrrev_i32_e32 v9, 31, v8
	v_lshl_add_u64 v[12:13], v[8:9], 2, s[16:17]
	v_or_b32_e32 v6, 48, v6
	v_ashrrev_i32_e32 v7, 31, v6
	v_lshlrev_b64 v[8:9], 11, v[8:9]
	v_lshlrev_b64 v[6:7], 11, v[6:7]
	v_lshl_add_u64 v[8:9], s[14:15], 0, v[8:9]
	v_lshl_add_u64 v[6:7], s[14:15], 0, v[6:7]
	v_lshl_add_u64 v[8:9], v[8:9], 0, v[16:17]
	v_lshl_add_u64 v[6:7], v[6:7], 0, v[16:17]
	s_mov_b32 s67, s64
	s_mov_b64 s[28:29], s[10:11]
	s_mov_b64 s[26:27], s[8:9]
	s_mov_b32 s66, s65
	s_waitcnt vmcnt(0)
	v_mul_f32_e32 v14, 0x3b800000, v158
	v_pk_mul_f32 v[142:143], v[142:143], v[14:15] op_sel_hi:[1,0]
	v_pk_mul_f32 v[144:145], v[144:145], v[14:15] op_sel_hi:[1,0]
	v_pk_mul_f32 v[138:139], v[138:139], v[14:15] op_sel_hi:[1,0]
	v_pk_mul_f32 v[140:141], v[140:141], v[14:15] op_sel_hi:[1,0]
	v_pk_mul_f32 v[126:127], v[126:127], v[14:15] op_sel_hi:[1,0]
	v_pk_mul_f32 v[128:129], v[128:129], v[14:15] op_sel_hi:[1,0]
	v_pk_mul_f32 v[122:123], v[122:123], v[14:15] op_sel_hi:[1,0]
	v_pk_mul_f32 v[14:15], v[124:125], v[14:15] op_sel_hi:[1,0]
	v_mul_f32_e32 v124, 0x3b800000, v159
	v_cvt_pk_bf16_f32 v126, v126, v127
	v_cvt_pk_bf16_f32 v127, v128, v129
	v_cvt_pk_bf16_f32 v122, v122, v123
	v_cvt_pk_bf16_f32 v123, v14, v15
	v_pk_mul_f32 v[14:15], v[134:135], v[124:125] op_sel_hi:[1,0]
	v_pk_mul_f32 v[128:129], v[136:137], v[124:125] op_sel_hi:[1,0]
	v_cvt_pk_bf16_f32 v142, v142, v143
	v_cvt_pk_bf16_f32 v143, v144, v145
	v_pk_mul_f32 v[130:131], v[130:131], v[124:125] op_sel_hi:[1,0]
	v_pk_mul_f32 v[132:133], v[132:133], v[124:125] op_sel_hi:[1,0]
	v_pk_mul_f32 v[118:119], v[118:119], v[124:125] op_sel_hi:[1,0]
	v_pk_mul_f32 v[120:121], v[120:121], v[124:125] op_sel_hi:[1,0]
	v_pk_mul_f32 v[114:115], v[114:115], v[124:125] op_sel_hi:[1,0]
	v_pk_mul_f32 v[116:117], v[116:117], v[124:125] op_sel_hi:[1,0]
	v_cvt_pk_bf16_f32 v14, v14, v15
	v_cvt_pk_bf16_f32 v15, v128, v129
	v_cvt_pk_bf16_f32 v138, v138, v139
	v_cvt_pk_bf16_f32 v139, v140, v141
	v_mov_b32_e32 v188, v142
	v_mov_b32_e32 v189, v143
	v_mov_b32_e32 v190, v138
	v_mov_b32_e32 v191, v139
	v_lshl_add_u64 v[162:163], v[4:5], 0, v[160:161]
	s_nop 0
	v_permlane16_swap_b32 v188, v190
	v_permlane16_swap_b32 v189, v191
	global_store_dwordx4 v[162:163], v[188:191], off
	v_mov_b32_e32 v192, v126
	v_mov_b32_e32 v193, v127
	v_mov_b32_e32 v194, v122
	v_mov_b32_e32 v195, v123
	v_lshl_add_u64 v[162:163], v[4:5], 0, v[160:161]
	s_nop 0
	v_permlane16_swap_b32 v192, v194
	v_permlane16_swap_b32 v193, v195
	global_store_dwordx4 v[162:163], v[192:195], off offset:256
	v_cvt_pk_bf16_f32 v122, v130, v131
	v_cvt_pk_bf16_f32 v123, v132, v133
	v_cvt_pk_bf16_f32 v118, v118, v119
	v_cvt_pk_bf16_f32 v119, v120, v121
	v_cvt_pk_bf16_f32 v114, v114, v115
	v_cvt_pk_bf16_f32 v115, v116, v117
	v_mov_b32_e32 v196, v14
	v_mov_b32_e32 v197, v15
	v_mov_b32_e32 v198, v122
	v_mov_b32_e32 v199, v123
	v_lshl_add_u64 v[162:163], v[10:11], 0, v[160:161]
	s_nop 0
	v_permlane16_swap_b32 v196, v198
	v_permlane16_swap_b32 v197, v199
	global_store_dwordx4 v[162:163], v[196:199], off
	v_mov_b32_e32 v200, v118
	v_mov_b32_e32 v201, v119
	v_mov_b32_e32 v202, v114
	v_mov_b32_e32 v203, v115
	v_lshl_add_u64 v[162:163], v[10:11], 0, v[160:161]
	s_nop 0
	v_permlane16_swap_b32 v200, v202
	v_permlane16_swap_b32 v201, v203
	global_store_dwordx4 v[162:163], v[200:203], off offset:256
	global_load_dword v10, v[12:13], off
	s_nop 0
	global_load_dword v11, v[2:3], off offset:192
	s_waitcnt vmcnt(0)
	v_mul_f32_e32 v10, 0x3b800000, v10
	v_mul_f32_e32 v12, 0x3b800000, v11
	v_pk_mul_f32 v[14:15], v[110:111], v[10:11] op_sel_hi:[1,0]
	v_pk_mul_f32 v[16:17], v[112:113], v[10:11] op_sel_hi:[1,0]
	v_pk_mul_f32 v[106:107], v[106:107], v[10:11] op_sel_hi:[1,0]
	v_pk_mul_f32 v[108:109], v[108:109], v[10:11] op_sel_hi:[1,0]
	v_pk_mul_f32 v[94:95], v[94:95], v[10:11] op_sel_hi:[1,0]
	v_pk_mul_f32 v[96:97], v[96:97], v[10:11] op_sel_hi:[1,0]
	v_pk_mul_f32 v[90:91], v[90:91], v[10:11] op_sel_hi:[1,0]
	v_pk_mul_f32 v[10:11], v[92:93], v[10:11] op_sel_hi:[1,0]
	v_pk_mul_f32 v[92:93], v[102:103], v[12:13] op_sel_hi:[1,0]
	v_pk_mul_f32 v[102:103], v[104:105], v[12:13] op_sel_hi:[1,0]
	v_pk_mul_f32 v[98:99], v[98:99], v[12:13] op_sel_hi:[1,0]
	v_pk_mul_f32 v[100:101], v[100:101], v[12:13] op_sel_hi:[1,0]
	v_pk_mul_f32 v[86:87], v[86:87], v[12:13] op_sel_hi:[1,0]
	v_pk_mul_f32 v[88:89], v[88:89], v[12:13] op_sel_hi:[1,0]
	v_pk_mul_f32 v[82:83], v[82:83], v[12:13] op_sel_hi:[1,0]
	v_pk_mul_f32 v[12:13], v[84:85], v[12:13] op_sel_hi:[1,0]
	v_cvt_pk_bf16_f32 v14, v14, v15
	v_cvt_pk_bf16_f32 v15, v16, v17
	v_cvt_pk_bf16_f32 v16, v106, v107
	v_cvt_pk_bf16_f32 v17, v108, v109
	v_cvt_pk_bf16_f32 v84, v94, v95
	v_cvt_pk_bf16_f32 v85, v96, v97
	v_cvt_pk_bf16_f32 v90, v90, v91
	v_cvt_pk_bf16_f32 v91, v10, v11
	v_cvt_pk_bf16_f32 v10, v92, v93
	v_cvt_pk_bf16_f32 v11, v102, v103
	v_cvt_pk_bf16_f32 v92, v98, v99
	v_cvt_pk_bf16_f32 v93, v100, v101
	v_cvt_pk_bf16_f32 v86, v86, v87
	v_cvt_pk_bf16_f32 v87, v88, v89
	v_cvt_pk_bf16_f32 v82, v82, v83
	v_cvt_pk_bf16_f32 v83, v12, v13
	v_mov_b32_e32 v204, v14
	v_mov_b32_e32 v205, v15
	v_mov_b32_e32 v206, v16
	v_mov_b32_e32 v207, v17
	v_lshl_add_u64 v[162:163], v[8:9], 0, v[160:161]
	s_nop 0
	v_permlane16_swap_b32 v204, v206
	v_permlane16_swap_b32 v205, v207
	global_store_dwordx4 v[162:163], v[204:207], off
	v_mov_b32_e32 v208, v84
	v_mov_b32_e32 v209, v85
	v_mov_b32_e32 v210, v90
	v_mov_b32_e32 v211, v91
	v_lshl_add_u64 v[162:163], v[8:9], 0, v[160:161]
	s_nop 0
	v_permlane16_swap_b32 v208, v210
	v_permlane16_swap_b32 v209, v211
	global_store_dwordx4 v[162:163], v[208:211], off offset:256
	v_mov_b32_e32 v212, v10
	v_mov_b32_e32 v213, v11
	v_mov_b32_e32 v214, v92
	v_mov_b32_e32 v215, v93
	v_lshl_add_u64 v[162:163], v[6:7], 0, v[160:161]
	s_nop 0
	v_permlane16_swap_b32 v212, v214
	v_permlane16_swap_b32 v213, v215
	global_store_dwordx4 v[162:163], v[212:215], off
	v_mov_b32_e32 v220, v86
	v_mov_b32_e32 v221, v87
	v_mov_b32_e32 v222, v82
	v_mov_b32_e32 v223, v83
	v_lshl_add_u64 v[162:163], v[6:7], 0, v[160:161]
	s_nop 0
	v_permlane16_swap_b32 v220, v222
	v_permlane16_swap_b32 v221, v223
	global_store_dwordx4 v[162:163], v[220:223], off offset:256
	global_load_dword v14, v[2:3], off offset:512
	global_load_dword v15, v[2:3], off offset:576
	v_add_co_u32_e32 v8, vcc, s60, v4
	v_lshl_add_u64 v[6:7], v[4:5], 0, s[20:21]
	s_nop 0
	v_addc_co_u32_e32 v9, vcc, 0, v5, vcc
	v_add_co_u32_e32 v12, vcc, s61, v4
	v_lshl_add_u64 v[10:11], v[4:5], 0, s[22:23]
	s_nop 0
	v_addc_co_u32_e32 v13, vcc, 0, v5, vcc
	s_and_b64 vcc, exec, s[6:7]
	s_waitcnt vmcnt(0)
	v_mul_f32_e32 v14, 0x3b800000, v14
	v_mul_f32_e32 v16, 0x3b800000, v15
	v_pk_mul_f32 v[78:79], v[78:79], v[14:15] op_sel_hi:[1,0]
	v_pk_mul_f32 v[80:81], v[80:81], v[14:15] op_sel_hi:[1,0]
	v_pk_mul_f32 v[74:75], v[74:75], v[14:15] op_sel_hi:[1,0]
	v_pk_mul_f32 v[76:77], v[76:77], v[14:15] op_sel_hi:[1,0]
	v_pk_mul_f32 v[62:63], v[62:63], v[14:15] op_sel_hi:[1,0]
	v_pk_mul_f32 v[64:65], v[64:65], v[14:15] op_sel_hi:[1,0]
	v_pk_mul_f32 v[58:59], v[58:59], v[14:15] op_sel_hi:[1,0]
	v_pk_mul_f32 v[14:15], v[60:61], v[14:15] op_sel_hi:[1,0]
	v_pk_mul_f32 v[60:61], v[70:71], v[16:17] op_sel_hi:[1,0]
	v_pk_mul_f32 v[70:71], v[72:73], v[16:17] op_sel_hi:[1,0]
	v_pk_mul_f32 v[66:67], v[66:67], v[16:17] op_sel_hi:[1,0]
	v_pk_mul_f32 v[68:69], v[68:69], v[16:17] op_sel_hi:[1,0]
	v_pk_mul_f32 v[54:55], v[54:55], v[16:17] op_sel_hi:[1,0]
	v_pk_mul_f32 v[56:57], v[56:57], v[16:17] op_sel_hi:[1,0]
	v_pk_mul_f32 v[50:51], v[50:51], v[16:17] op_sel_hi:[1,0]
	v_pk_mul_f32 v[16:17], v[52:53], v[16:17] op_sel_hi:[1,0]
	v_cvt_pk_bf16_f32 v52, v78, v79
	v_cvt_pk_bf16_f32 v53, v80, v81
	v_cvt_pk_bf16_f32 v72, v74, v75
	v_cvt_pk_bf16_f32 v73, v76, v77
	v_cvt_pk_bf16_f32 v62, v62, v63
	v_cvt_pk_bf16_f32 v63, v64, v65
	v_cvt_pk_bf16_f32 v58, v58, v59
	v_cvt_pk_bf16_f32 v59, v14, v15
	v_cvt_pk_bf16_f32 v14, v60, v61
	v_cvt_pk_bf16_f32 v15, v70, v71
	v_cvt_pk_bf16_f32 v60, v66, v67
	v_cvt_pk_bf16_f32 v61, v68, v69
	v_cvt_pk_bf16_f32 v54, v54, v55
	v_cvt_pk_bf16_f32 v55, v56, v57
	v_cvt_pk_bf16_f32 v50, v50, v51
	v_cvt_pk_bf16_f32 v51, v16, v17
	global_store_dwordx2 v[8:9], v[52:53], off
	global_store_dwordx2 v[6:7], v[72:73], off offset:32
	v_mov_b32_e32 v224, v62
	v_mov_b32_e32 v225, v63
	v_mov_b32_e32 v226, v58
	v_mov_b32_e32 v227, v59
	v_lshl_add_u64 v[162:163], v[6:7], 0, v[160:161]
	s_nop 0
	v_permlane16_swap_b32 v224, v226
	v_permlane16_swap_b32 v225, v227
	global_store_dwordx4 v[162:163], v[224:227], off offset:256
	global_store_dwordx2 v[12:13], v[14:15], off
	global_store_dwordx2 v[10:11], v[60:61], off offset:32
	v_mov_b32_e32 v228, v54
	v_mov_b32_e32 v229, v55
	v_mov_b32_e32 v230, v50
	v_mov_b32_e32 v231, v51
	v_lshl_add_u64 v[162:163], v[10:11], 0, v[160:161]
	s_nop 0
	v_permlane16_swap_b32 v228, v230
	v_permlane16_swap_b32 v229, v231
	global_store_dwordx4 v[162:163], v[228:231], off offset:256
	global_load_dword v10, v[2:3], off offset:640
	s_nop 0
	global_load_dword v11, v[2:3], off offset:704
	v_add_co_u32_e64 v6, s[6:7], s62, v4
	v_lshl_add_u64 v[2:3], v[4:5], 0, s[24:25]
	s_nop 0
	v_addc_co_u32_e64 v7, s[6:7], 0, v5, s[6:7]
	v_lshl_add_u64 v[8:9], v[4:5], 0, s[12:13]
	v_add_co_u32_e64 v4, s[6:7], s63, v4
	s_waitcnt vmcnt(0)
	v_mul_f32_e32 v10, 0x3b800000, v10
	v_mul_f32_e32 v12, 0x3b800000, v11
	v_pk_mul_f32 v[14:15], v[46:47], v[10:11] op_sel_hi:[1,0]
	v_pk_mul_f32 v[16:17], v[48:49], v[10:11] op_sel_hi:[1,0]
	v_pk_mul_f32 v[42:43], v[42:43], v[10:11] op_sel_hi:[1,0]
	v_pk_mul_f32 v[44:45], v[44:45], v[10:11] op_sel_hi:[1,0]
	v_pk_mul_f32 v[30:31], v[30:31], v[10:11] op_sel_hi:[1,0]
	v_pk_mul_f32 v[32:33], v[32:33], v[10:11] op_sel_hi:[1,0]
	v_pk_mul_f32 v[26:27], v[26:27], v[10:11] op_sel_hi:[1,0]
	v_pk_mul_f32 v[10:11], v[28:29], v[10:11] op_sel_hi:[1,0]
	v_pk_mul_f32 v[28:29], v[38:39], v[12:13] op_sel_hi:[1,0]
	v_pk_mul_f32 v[38:39], v[40:41], v[12:13] op_sel_hi:[1,0]
	v_pk_mul_f32 v[34:35], v[34:35], v[12:13] op_sel_hi:[1,0]
	v_pk_mul_f32 v[36:37], v[36:37], v[12:13] op_sel_hi:[1,0]
	v_pk_mul_f32 v[22:23], v[22:23], v[12:13] op_sel_hi:[1,0]
	v_pk_mul_f32 v[24:25], v[24:25], v[12:13] op_sel_hi:[1,0]
	v_pk_mul_f32 v[18:19], v[18:19], v[12:13] op_sel_hi:[1,0]
	v_pk_mul_f32 v[12:13], v[20:21], v[12:13] op_sel_hi:[1,0]
	v_cvt_pk_bf16_f32 v14, v14, v15
	v_cvt_pk_bf16_f32 v15, v16, v17
	v_addc_co_u32_e64 v5, s[6:7], 0, v5, s[6:7]
	v_cvt_pk_bf16_f32 v16, v42, v43
	v_cvt_pk_bf16_f32 v17, v44, v45
	v_cvt_pk_bf16_f32 v20, v30, v31
	v_cvt_pk_bf16_f32 v21, v32, v33
	v_cvt_pk_bf16_f32 v26, v26, v27
	v_cvt_pk_bf16_f32 v27, v10, v11
	v_cvt_pk_bf16_f32 v10, v28, v29
	v_cvt_pk_bf16_f32 v11, v38, v39
	v_cvt_pk_bf16_f32 v28, v34, v35
	v_cvt_pk_bf16_f32 v29, v36, v37
	v_cvt_pk_bf16_f32 v22, v22, v23
	v_cvt_pk_bf16_f32 v23, v24, v25
	v_cvt_pk_bf16_f32 v18, v18, v19
	v_cvt_pk_bf16_f32 v19, v12, v13
	global_store_dwordx2 v[6:7], v[14:15], off
	global_store_dwordx2 v[2:3], v[16:17], off offset:32
	v_mov_b32_e32 v232, v20
	v_mov_b32_e32 v233, v21
	v_mov_b32_e32 v234, v26
	v_mov_b32_e32 v235, v27
	v_lshl_add_u64 v[162:163], v[2:3], 0, v[160:161]
	s_nop 0
	v_permlane16_swap_b32 v232, v234
	v_permlane16_swap_b32 v233, v235
	global_store_dwordx4 v[162:163], v[232:235], off offset:256
	global_store_dwordx2 v[4:5], v[10:11], off
	global_store_dwordx2 v[8:9], v[28:29], off offset:32
	v_mov_b32_e32 v188, v22
	v_mov_b32_e32 v189, v23
	v_mov_b32_e32 v190, v18
	v_mov_b32_e32 v191, v19
	v_lshl_add_u64 v[162:163], v[8:9], 0, v[160:161]
	s_nop 0
	v_permlane16_swap_b32 v188, v190
	v_permlane16_swap_b32 v189, v191
	global_store_dwordx4 v[162:163], v[188:191], off offset:256
	s_cbranch_vccz .LBB0_5681
	s_waitcnt vmcnt(0)
	s_cmpk_gt_u32 s3, 0xff
	s_cbranch_scc1 .LBB0_5696
	s_barrier
